# MLA attention: waves 4-7 run half a step behind waves 0-3 (second barrier per key tile, role flag in s100)
# speedup vs baseline: 1.0007x; 1.0007x over previous
; __device__ __forceinline__ int opaque_tid() { int t = threadIdx.x; asm volatile("" : "+v"(t)); return t; }
; #define DMA_K(t, slot) do { const bf16_t* s_ = Knp + (long)(t) * (KVBLK * LDK); const unsigned d_ = (unsigned)__builtin_amdgcn_readfirstlane(kn_dst + (slot) * SHM_KN); \
;     glds16s(s_, kn_off, d_); glds16s(s_ + 16 * LDK, kn_off, d_ + 4096); glds16s(Krp + (long)(t) * (KVBLK * 64), kr_off, (unsigned)__builtin_amdgcn_readfirstlane(kr_dst + (slot) * SHM_KR)); } while (0)
; #define DMA_V(t, slot) do { const bf16_t* s_ = Vp + (long)(t) * (KVBLK * LDK); const unsigned d_ = (unsigned)__builtin_amdgcn_readfirstlane(v_dst + (slot) * SHM_V); \
;     glds16s(s_, v_off, d_); glds16s(s_ + 32 * LDK, v_off, d_ + 8192); } while (0)
; __device__ __forceinline__ void mla_unit(char* lds, const bf16_t* __restrict__ Qp, const bf16_t* __restrict__ Knp, const bf16_t* __restrict__ Vp, ...
;     ...
;   const int tid = opaque_tid(), wid = __builtin_amdgcn_readfirstlane(tid >> 6), lane = tid & 63, r32 = lane & 31, hi = lane >> 5;
;   float* wsf = (float*)(lds + P_WS) + wid * 64; float* li_l = wsf; float* al_l = wsf + 32;
;   const unsigned lds0 = (unsigned)(uintptr_t)lds;
;   const int pk = (wid & 3) + 8 * (wid >> 2);
;   const int krow_n = 4 * pk + (lane >> 4);
;   const unsigned kn_off = (unsigned)(krow_n * LDK + (((lane & 15) ^ (krow_n & 15)) << 3)) * 2u;
;   const int krow_r = 8 * wid + (lane >> 3);
;   const unsigned kr_off = (unsigned)(krow_r * 64 + (((lane & 7) ^ ((krow_r >> 1) & 7)) << 3)) * 2u;
;   const int vst_ = 2 * wid + (lane >> 5), vkk = (vst_ >> 2) * 8 + ((lane >> 2) & 7), vkey = (vkk & ~0xC) | ((vkk & 4) << 1) | ((vkk & 8) >> 1), vcol = (vst_ & 3) * 32 + (lane & 3) * 8;
;   const unsigned v_off = (unsigned)(vkey * LDK + vcol) * 2u;
;   const unsigned kn_dst = lds0 + P_KN + pk * 1024, kr_dst = lds0 + P_KR + wid * 1024, v_dst = lds0 + P_V + wid * 1024;
;     ...
;   if (first) { DMA_K(0, 0); DMA_V(0, 0); DMA_K(1, 1); DMA_V(1, 1); DMA_K(2, 2); }
.LBB0_236:
	v_mov_b32_e32 v50, v252
	s_ashr_i32 s6, s74, 9
	v_readfirstlane_b32 s0, v50
	s_ashr_i32 s8, s0, 6
	s_lshr_b32 s100, s8, 2
	s_ashr_i32 s5, s0, 5
	s_and_b32 s1, s8, 3
	s_and_b32 s5, s5, -8
	s_or_b32 s1, s1, s5
	s_lshl_b32 s5, s1, 2
	s_ashr_i32 s12, s0, 4
	v_bfe_u32 v1, v50, 4, 2
	s_ashr_i32 s7, s6, 31
	s_and_b32 s13, s12, 0x7ffff0
	s_lshr_b32 s12, s12, 1
	v_or_b32_e32 v2, s5, v1
	v_bitop3_b32 v1, s5, v50, v1 bitop3:0x36
	s_bfe_u32 s38, s74, 0x40005
	s_lshl_b64 s[30:31], s[6:7], 22
	s_lshl_b64 s[36:37], s[6:7], 20
	s_lshl_b32 s9, s8, 1
	s_and_b32 s12, s12, 4
	s_lshl_b32 s72, s1, 10
	v_lshlrev_b32_e32 v2, 9, v2
	v_lshlrev_b32_e32 v1, 4, v1
	s_cmp_lg_u32 0, -1
	v_and_or_b32 v197, v1, s53, v2
	v_bfe_u32 v1, v50, 3, 3
	s_cselect_b32 s1, 0, 0
	s_lshl_b32 s71, s8, 10
	v_lshl_or_b32 v1, s8, 3, v1
	s_add_i32 s14, s1, s72
	s_add_i32 s73, s71, s1
	v_lshlrev_b32_e32 v2, 7, v1
	v_lshrrev_b32_e32 v1, 1, v1
	s_add_i32 s76, s14, 0xc000
	s_add_i32 s75, s73, 0x18000
	v_readlane_b32 s1, v253, 3
	v_xor_b32_e32 v1, v1, v50
	s_cmp_lg_u32 s74, s1
	v_lshlrev_b32_e32 v1, 4, v1
	s_movk_i32 s1, 0x70
	v_and_or_b32 v198, v1, s1, v2
	v_lshrrev_b32_e32 v1, 2, v50
	v_lshrrev_b32_e32 v2, 1, v50
	v_bfe_u32 v49, v50, 5, 1
	v_and_or_b32 v1, v1, 3, s13
	v_and_b32_e32 v2, 8, v2
	v_lshlrev_b32_e32 v48, 4, v50
	v_or3_b32 v1, v1, v2, s12
	v_and_or_b32 v2, s9, 2, v49
	v_and_b32_e32 v3, 48, v48
	v_lshl_or_b32 v2, v2, 6, v3
	v_lshl_or_b32 v199, v1, 9, v2
	s_cbranch_scc1 .LBB0_238
	s_lshl_b32 s1, s38, 23
	v_readlane_b32 s5, v254, 62
	s_add_u32 s1, s5, s1
	v_readlane_b32 s5, v254, 63
	s_addc_u32 s5, s5, 0
	s_add_u32 s12, s1, s30
	s_addc_u32 s13, s5, s31
	s_add_u32 s14, s12, 0x100
	s_addc_u32 s15, s13, 0
	s_add_u32 s16, s26, s36
	s_addc_u32 s17, s27, s37
	s_mov_b32 s1, m0
	s_mov_b32 m0, s76
	s_nop 0
	global_load_lds_dwordx4 v197, s[12:13]
	s_mov_b32 m0, s1
	s_add_u32 s18, s12, 0x2000
	s_addc_u32 s19, s13, 0
	s_add_i32 s1, s76, 0x1000
	s_mov_b32 s5, m0
	s_mov_b32 m0, s1
	s_nop 0
	global_load_lds_dwordx4 v197, s[18:19]
	s_mov_b32 m0, s5
	s_mov_b32 s1, m0
	s_mov_b32 m0, s75
	s_nop 0
	global_load_lds_dwordx4 v198, s[16:17]
	s_mov_b32 m0, s1
	s_nop 0
	s_mov_b32 s1, m0
	s_mov_b32 m0, s73
	s_nop 0
	global_load_lds_dwordx4 v199, s[14:15]
	s_mov_b32 m0, s1
	s_add_u32 s14, s12, 0x4100
	s_addc_u32 s15, s13, 0
	s_add_i32 s1, s73, 0x2000
	s_mov_b32 s5, m0
	s_mov_b32 m0, s1
	s_nop 0
	global_load_lds_dwordx4 v199, s[14:15]
	s_mov_b32 m0, s5
	s_add_u32 s14, s12, 0x8000
	s_addc_u32 s15, s13, 0
	s_cmp_lg_u32 0, -1
	s_cselect_b32 s1, 0, 0
	s_add_i32 s5, s1, s72
	s_add_i32 s9, s5, 0x10000
	s_mov_b32 s18, m0
	s_mov_b32 m0, s9
	s_nop 0
	global_load_lds_dwordx4 v197, s[14:15]
	s_mov_b32 m0, s18
	s_add_u32 s14, s12, 0xa000
	s_addc_u32 s15, s13, 0
	s_add_i32 s9, s5, 0x11000
	s_mov_b32 s18, m0
	s_mov_b32 m0, s9
	s_nop 0
	global_load_lds_dwordx4 v197, s[14:15]
	s_mov_b32 m0, s18
	s_add_u32 s14, s16, 0x2000
	s_addc_u32 s15, s17, 0
	s_add_i32 s1, s1, s71
	s_add_i32 s9, s1, 0x1a000
	s_mov_b32 s18, m0
	s_mov_b32 m0, s9
	s_nop 0
	global_load_lds_dwordx4 v198, s[14:15]
	s_mov_b32 m0, s18
	s_add_u32 s14, s12, 0x8100
	s_addc_u32 s15, s13, 0
	s_add_i32 s9, s1, 0x4000
	s_mov_b32 s18, m0
	s_mov_b32 m0, s9
	s_nop 0
	global_load_lds_dwordx4 v199, s[14:15]
	s_mov_b32 m0, s18
	s_add_u32 s14, s12, 0xc100
	s_addc_u32 s15, s13, 0
	s_add_i32 s9, s1, 0x6000
	s_mov_b32 s18, m0
	s_mov_b32 m0, s9
	s_nop 0
	global_load_lds_dwordx4 v199, s[14:15]
	s_mov_b32 m0, s18
	s_add_u32 s14, s12, 0x10000
	s_addc_u32 s15, s13, 0
	s_add_i32 s9, s5, 0x14000
	s_add_u32 s12, s12, 0x12000
	s_mov_b32 s18, m0
	s_mov_b32 m0, s9
	s_nop 0
	global_load_lds_dwordx4 v197, s[14:15]
	s_mov_b32 m0, s18
	s_addc_u32 s13, s13, 0
	s_add_i32 s5, s5, 0x15000
	s_mov_b32 s9, m0
	s_mov_b32 m0, s5
	s_nop 0
	global_load_lds_dwordx4 v197, s[12:13]
	s_mov_b32 m0, s9
	s_add_u32 s12, s16, 0x4000
	s_addc_u32 s13, s17, 0
	s_add_i32 s1, s1, 0x1c000
	s_mov_b32 s5, m0
	s_mov_b32 m0, s1
	s_nop 0
	global_load_lds_dwordx4 v198, s[12:13]
	s_mov_b32 m0, s5
.LBB0_238:
	s_lshl_b32 s1, s74, 8
	s_lshl_b64 s[64:65], s[6:7], 13
	s_and_b32 s1, s1, 0x1f00
	s_or_b32 s64, s64, s1
	s_mul_hi_u32 s6, s64, 0x1800
	s_mul_i32 s7, s65, 0x1800
	s_mul_i32 s5, s64, 0x1800
	s_add_i32 s6, s6, s7
	v_readlane_b32 s7, v254, 60
	s_add_u32 s5, s7, s5
	v_readlane_b32 s7, v254, 61
	s_addc_u32 s7, s7, s6
	s_mul_i32 s6, s38, 0x180
	s_add_u32 s6, s5, s6
	s_addc_u32 s7, s7, 0
	v_and_b32_e32 v196, 31, v50
	s_lshl_b32 s39, s8, 5
	v_or_b32_e32 v1, s39, v196
	v_mov_b64_e32 v[2:3], s[6:7]
	s_movk_i32 s5, 0x1800
	v_mad_i64_i32 v[2:3], s[6:7], v1, s5, v[2:3]
	v_lshlrev_b32_e32 v194, 4, v49
	v_mov_b32_e32 v195, v0
	v_lshl_add_u64 v[2:3], v[2:3], 0, v[194:195]
	global_load_dwordx4 v[4:7], v[2:3], off
	s_mov_b32 s6, 0x3dd53b94
	v_lshlrev_b32_e32 v204, 8, v196
	v_and_b32_e32 v51, 0xf0, v48
	v_add_u32_e32 v66, 0, v204
	s_waitcnt vmcnt(9)
	v_xad_u32 v56, v194, v51, v66
	v_lshlrev_b32_e32 v205, 7, v196
	s_and_b32 s0, s0, 0x3fffffc0
	s_lshl_b32 s0, s0, 2
	s_add_i32 s33, s0, 0
	s_add_i32 s33, s33, 0x1e000
	v_lshl_add_u32 v200, v196, 2, s33
	s_waitcnt vmcnt(0)
	v_lshlrev_b32_e32 v1, 16, v4
	v_and_b32_e32 v4, 0xffff0000, v4
	v_lshlrev_b32_e32 v8, 16, v5
	v_and_b32_e32 v5, 0xffff0000, v5
	v_lshlrev_b32_e32 v9, 16, v6
	v_and_b32_e32 v6, 0xffff0000, v6
	v_lshlrev_b32_e32 v10, 16, v7
	v_and_b32_e32 v7, 0xffff0000, v7
	v_mul_f32_e32 v4, 0x3dd53b94, v4
	v_mul_f32_e32 v5, 0x3dd53b94, v5
	v_mul_f32_e32 v6, 0x3dd53b94, v6
	v_mul_f32_e32 v7, 0x3dd53b94, v7
	v_mul_f32_e32 v1, 0x3dd53b94, v1
	v_mul_f32_e32 v8, 0x3dd53b94, v8
	v_mul_f32_e32 v9, 0x3dd53b94, v9
	v_mul_f32_e32 v10, 0x3dd53b94, v10
	v_cvt_pk_bf16_f32 v130, v1, v4
	v_cvt_pk_bf16_f32 v131, v8, v5
	v_cvt_pk_bf16_f32 v132, v9, v6
	v_cvt_pk_bf16_f32 v133, v10, v7
	global_load_dwordx4 v[4:7], v[2:3], off offset:32
	s_waitcnt vmcnt(0)
; __device__ __forceinline__ float bf2f(unsigned h) { return __uint_as_float(h << 16); }
; __device__ __forceinline__ void mla_unit(char* lds, const bf16_t* __restrict__ Qp, const bf16_t* __restrict__ Knp, const bf16_t* __restrict__ Vp, ...
;     ...
;   for (int d0 = 0; d0 < 8; ++d0) { const u32x4 raw = *reinterpret_cast<const u32x4*>(Qw + d0 * 16); u32x4 w;
; #pragma unroll
;     for (int p = 0; p < 4; ++p) w[p] = cvtpk(bf2f(raw[p] & 0xffffu) * C, bf2f(raw[p] >> 16) * C);
;     qr[d0] = *reinterpret_cast<bf16x8*>(&w); }
;   { const int pos = pos0 + wid * QBLK + r32;
; #pragma unroll
;     for (int d0 = 0; d0 < 4; ++d0) {
;       const u32x4 raw = *reinterpret_cast<const u32x4*>(Qw + 128 + d0 * 16);
;       const int i0 = d0 * 8 + hi * 4;
;       const f32x4 cc = *reinterpret_cast<const f32x4*>(cs_tab + pos * 32 + i0) * C, ss = *reinterpret_cast<const f32x4*>(sn_tab + pos * 32 + i0) * C;
;       u32x4 w;
; #pragma unroll
;       for (int p = 0; p < 4; ++p) { const float x1 = bf2f(raw[p] & 0xffffu), x2 = bf2f(raw[p] >> 16); w[p] = cvtpk(x1 * cc[p] - x2 * ss[p], x1 * ss[p] + x2 * cc[p]); }
;       qr[8 + d0] = *reinterpret_cast<bf16x8*>(&w);
;     } }
	v_lshlrev_b32_e32 v1, 16, v4
	v_and_b32_e32 v4, 0xffff0000, v4
	v_lshlrev_b32_e32 v8, 16, v5
	v_and_b32_e32 v5, 0xffff0000, v5
	v_lshlrev_b32_e32 v9, 16, v6
	v_and_b32_e32 v6, 0xffff0000, v6
	v_lshlrev_b32_e32 v10, 16, v7
	v_and_b32_e32 v7, 0xffff0000, v7
	v_mul_f32_e32 v4, 0x3dd53b94, v4
	v_mul_f32_e32 v5, 0x3dd53b94, v5
	v_mul_f32_e32 v6, 0x3dd53b94, v6
	v_mul_f32_e32 v7, 0x3dd53b94, v7
	v_mul_f32_e32 v1, 0x3dd53b94, v1
	v_mul_f32_e32 v8, 0x3dd53b94, v8
	v_mul_f32_e32 v9, 0x3dd53b94, v9
	v_mul_f32_e32 v10, 0x3dd53b94, v10
	v_cvt_pk_bf16_f32 v134, v1, v4
	v_cvt_pk_bf16_f32 v135, v8, v5
	v_cvt_pk_bf16_f32 v136, v9, v6
	v_cvt_pk_bf16_f32 v137, v10, v7
	global_load_dwordx4 v[4:7], v[2:3], off offset:64
	s_waitcnt vmcnt(0)
	v_lshlrev_b32_e32 v1, 16, v4
	v_and_b32_e32 v4, 0xffff0000, v4
	v_lshlrev_b32_e32 v8, 16, v5
	v_and_b32_e32 v5, 0xffff0000, v5
	v_lshlrev_b32_e32 v9, 16, v6
	v_and_b32_e32 v6, 0xffff0000, v6
	v_lshlrev_b32_e32 v10, 16, v7
	v_and_b32_e32 v7, 0xffff0000, v7
	v_mul_f32_e32 v4, 0x3dd53b94, v4
	v_mul_f32_e32 v5, 0x3dd53b94, v5
	v_mul_f32_e32 v6, 0x3dd53b94, v6
	v_mul_f32_e32 v7, 0x3dd53b94, v7
	v_mul_f32_e32 v1, 0x3dd53b94, v1
	v_mul_f32_e32 v8, 0x3dd53b94, v8
	v_mul_f32_e32 v9, 0x3dd53b94, v9
	v_mul_f32_e32 v10, 0x3dd53b94, v10
	v_cvt_pk_bf16_f32 v138, v1, v4
	v_cvt_pk_bf16_f32 v139, v8, v5
	v_cvt_pk_bf16_f32 v140, v9, v6
	v_cvt_pk_bf16_f32 v141, v10, v7
	global_load_dwordx4 v[4:7], v[2:3], off offset:96
	s_waitcnt vmcnt(0)
	v_lshlrev_b32_e32 v1, 16, v4
	v_and_b32_e32 v4, 0xffff0000, v4
	v_lshlrev_b32_e32 v8, 16, v5
	v_and_b32_e32 v5, 0xffff0000, v5
	v_lshlrev_b32_e32 v9, 16, v6
	v_and_b32_e32 v6, 0xffff0000, v6
	v_lshlrev_b32_e32 v10, 16, v7
	v_and_b32_e32 v7, 0xffff0000, v7
	v_mul_f32_e32 v4, 0x3dd53b94, v4
	v_mul_f32_e32 v5, 0x3dd53b94, v5
	v_mul_f32_e32 v6, 0x3dd53b94, v6
	v_mul_f32_e32 v7, 0x3dd53b94, v7
	v_mul_f32_e32 v1, 0x3dd53b94, v1
	v_mul_f32_e32 v8, 0x3dd53b94, v8
	v_mul_f32_e32 v9, 0x3dd53b94, v9
	v_mul_f32_e32 v10, 0x3dd53b94, v10
	v_cvt_pk_bf16_f32 v142, v1, v4
	v_cvt_pk_bf16_f32 v143, v8, v5
	v_cvt_pk_bf16_f32 v144, v9, v6
	v_cvt_pk_bf16_f32 v145, v10, v7
	global_load_dwordx4 v[4:7], v[2:3], off offset:128
	s_waitcnt vmcnt(0)
	v_lshlrev_b32_e32 v1, 16, v4
	v_and_b32_e32 v4, 0xffff0000, v4
	v_lshlrev_b32_e32 v8, 16, v5
	v_and_b32_e32 v5, 0xffff0000, v5
	v_lshlrev_b32_e32 v9, 16, v6
	v_and_b32_e32 v6, 0xffff0000, v6
	v_lshlrev_b32_e32 v10, 16, v7
	v_and_b32_e32 v7, 0xffff0000, v7
	v_mul_f32_e32 v4, 0x3dd53b94, v4
	v_mul_f32_e32 v5, 0x3dd53b94, v5
	v_mul_f32_e32 v6, 0x3dd53b94, v6
	v_mul_f32_e32 v7, 0x3dd53b94, v7
	v_mul_f32_e32 v1, 0x3dd53b94, v1
	v_mul_f32_e32 v8, 0x3dd53b94, v8
	v_mul_f32_e32 v9, 0x3dd53b94, v9
	v_mul_f32_e32 v10, 0x3dd53b94, v10
	v_cvt_pk_bf16_f32 v154, v1, v4
	v_cvt_pk_bf16_f32 v155, v8, v5
	v_cvt_pk_bf16_f32 v156, v9, v6
	v_cvt_pk_bf16_f32 v157, v10, v7
	global_load_dwordx4 v[4:7], v[2:3], off offset:160
	s_waitcnt vmcnt(0)
	v_lshlrev_b32_e32 v1, 16, v4
	v_and_b32_e32 v4, 0xffff0000, v4
	v_lshlrev_b32_e32 v8, 16, v5
	v_and_b32_e32 v5, 0xffff0000, v5
	v_lshlrev_b32_e32 v9, 16, v6
	v_and_b32_e32 v6, 0xffff0000, v6
	v_lshlrev_b32_e32 v10, 16, v7
	v_and_b32_e32 v7, 0xffff0000, v7
	v_mul_f32_e32 v4, 0x3dd53b94, v4
	v_mul_f32_e32 v5, 0x3dd53b94, v5
	v_mul_f32_e32 v6, 0x3dd53b94, v6
	v_mul_f32_e32 v7, 0x3dd53b94, v7
	v_mul_f32_e32 v1, 0x3dd53b94, v1
	v_mul_f32_e32 v8, 0x3dd53b94, v8
	v_mul_f32_e32 v9, 0x3dd53b94, v9
	v_mul_f32_e32 v10, 0x3dd53b94, v10
	v_cvt_pk_bf16_f32 v150, v1, v4
	v_cvt_pk_bf16_f32 v151, v8, v5
	v_cvt_pk_bf16_f32 v152, v9, v6
	v_cvt_pk_bf16_f32 v153, v10, v7
	global_load_dwordx4 v[4:7], v[2:3], off offset:192
	s_waitcnt vmcnt(0)
	v_lshlrev_b32_e32 v8, 16, v5
	v_lshlrev_b32_e32 v9, 16, v6
	v_and_b32_e32 v6, 0xffff0000, v6
	v_lshlrev_b32_e32 v10, 16, v7
	v_and_b32_e32 v7, 0xffff0000, v7
	v_lshlrev_b32_e32 v1, 16, v4
	v_and_b32_e32 v4, 0xffff0000, v4
	v_and_b32_e32 v5, 0xffff0000, v5
	v_mul_f32_e32 v8, 0x3dd53b94, v8
	v_mul_f32_e32 v9, 0x3dd53b94, v9
	v_mul_f32_e32 v6, 0x3dd53b94, v6
	v_mul_f32_e32 v7, 0x3dd53b94, v7
	v_mul_f32_e32 v1, 0x3dd53b94, v1
	v_mul_f32_e32 v4, 0x3dd53b94, v4
	v_mul_f32_e32 v5, 0x3dd53b94, v5
	v_mul_f32_e32 v10, 0x3dd53b94, v10
	v_cvt_pk_bf16_f32 v146, v1, v4
	v_cvt_pk_bf16_f32 v147, v8, v5
	v_cvt_pk_bf16_f32 v148, v9, v6
	v_cvt_pk_bf16_f32 v149, v10, v7
	global_load_dwordx4 v[6:9], v[2:3], off offset:224
	v_or_b32_e32 v1, s1, v196
	v_add_lshl_u32 v4, v1, s39, 5
	v_ashrrev_i32_e32 v5, 31, v4
	v_lshlrev_b64 v[4:5], 2, v[4:5]
	v_lshl_add_u64 v[10:11], s[34:35], 0, v[4:5]
	v_lshl_add_u64 v[12:13], s[86:87], 0, v[4:5]
	v_lshl_add_u64 v[4:5], v[10:11], 0, v[194:195]
	v_lshl_add_u64 v[18:19], v[12:13], 0, v[194:195]
	s_add_i32 s1, 0, 0x18000
	v_add_u32_e32 v206, s1, v205
	s_waitcnt vmcnt(0)
	v_lshlrev_b32_e32 v1, 16, v6
	v_and_b32_e32 v6, 0xffff0000, v6
	v_lshlrev_b32_e32 v10, 16, v7
	v_and_b32_e32 v7, 0xffff0000, v7
	v_lshlrev_b32_e32 v11, 16, v8
	v_and_b32_e32 v8, 0xffff0000, v8
	v_lshlrev_b32_e32 v14, 16, v9
	v_and_b32_e32 v9, 0xffff0000, v9
	v_mul_f32_e32 v6, 0x3dd53b94, v6
	v_mul_f32_e32 v10, 0x3dd53b94, v10
	v_mul_f32_e32 v7, 0x3dd53b94, v7
	v_mul_f32_e32 v11, 0x3dd53b94, v11
	v_mul_f32_e32 v8, 0x3dd53b94, v8
	v_mul_f32_e32 v14, 0x3dd53b94, v14
	v_mul_f32_e32 v9, 0x3dd53b94, v9
	v_mul_f32_e32 v1, 0x3dd53b94, v1
	v_cvt_pk_bf16_f32 v158, v1, v6
	v_cvt_pk_bf16_f32 v159, v10, v7
	v_cvt_pk_bf16_f32 v160, v11, v8
	v_cvt_pk_bf16_f32 v161, v14, v9
	global_load_dwordx4 v[6:9], v[2:3], off offset:256
	global_load_dwordx4 v[10:13], v[4:5], off
	global_load_dwordx4 v[14:17], v[18:19], off
	s_waitcnt vmcnt(1)
	v_mov_b32_e32 v22, v10
	s_waitcnt vmcnt(0)
; __device__ __forceinline__ float bf2f(unsigned h) { return __uint_as_float(h << 16); }
; __device__ __forceinline__ void mla_unit(char* lds, const bf16_t* __restrict__ Qp, const bf16_t* __restrict__ Knp, const bf16_t* __restrict__ Vp, ...
;     ...
;   { const int pos = pos0 + wid * QBLK + r32;
; #pragma unroll
;     for (int d0 = 0; d0 < 4; ++d0) {
;       const u32x4 raw = *reinterpret_cast<const u32x4*>(Qw + 128 + d0 * 16);
;       const int i0 = d0 * 8 + hi * 4;
;       const f32x4 cc = *reinterpret_cast<const f32x4*>(cs_tab + pos * 32 + i0) * C, ss = *reinterpret_cast<const f32x4*>(sn_tab + pos * 32 + i0) * C;
;       u32x4 w;
; #pragma unroll
;       for (int p = 0; p < 4; ++p) { const float x1 = bf2f(raw[p] & 0xffffu), x2 = bf2f(raw[p] >> 16); w[p] = cvtpk(x1 * cc[p] - x2 * ss[p], x1 * ss[p] + x2 * cc[p]); }
;       qr[8 + d0] = *reinterpret_cast<bf16x8*>(&w);
;     } }
;   f32x16 pA0, pA1, pB0, pB1; bf16x8 pa0, pa1, pa2, pa3;
;   constexpr float THRL = THR * 1.4426950408889634f;
;   float mhat = 0.f; f32x16 negm = f32x16{}; asm volatile("" : "+v"(negm));
	v_mov_b32_e32 v23, v14
	v_mov_b32_e32 v14, v11
	v_mov_b32_e32 v24, v12
	v_mov_b32_e32 v25, v16
	v_mov_b32_e32 v16, v13
	v_lshlrev_b32_e32 v20, 16, v6
	v_and_b32_e32 v21, 0xffff0000, v6
	v_lshlrev_b32_e32 v6, 16, v7
	v_and_b32_e32 v7, 0xffff0000, v7
	v_lshlrev_b32_e32 v10, 16, v8
	v_and_b32_e32 v11, 0xffff0000, v8
	v_lshlrev_b32_e32 v8, 16, v9
	v_and_b32_e32 v9, 0xffff0000, v9
	v_pk_mul_f32 v[12:13], v[22:23], s[6:7] op_sel_hi:[1,0]
	v_pk_mul_f32 v[14:15], v[14:15], s[6:7] op_sel_hi:[1,0]
	v_pk_mul_f32 v[22:23], v[24:25], s[6:7] op_sel_hi:[1,0]
	v_pk_mul_f32 v[16:17], v[16:17], s[6:7] op_sel_hi:[1,0]
	v_pk_mul_f32 v[24:25], v[12:13], v[20:21]
	v_pk_mul_f32 v[12:13], v[12:13], v[20:21] op_sel:[0,1] op_sel_hi:[1,0]
	v_pk_mul_f32 v[20:21], v[14:15], v[6:7]
	v_pk_mul_f32 v[6:7], v[14:15], v[6:7] op_sel:[0,1] op_sel_hi:[1,0]
	v_pk_mul_f32 v[14:15], v[22:23], v[10:11]
	v_pk_mul_f32 v[10:11], v[22:23], v[10:11] op_sel:[0,1] op_sel_hi:[1,0]
	v_pk_mul_f32 v[22:23], v[16:17], v[8:9]
	v_pk_mul_f32 v[8:9], v[16:17], v[8:9] op_sel:[0,1] op_sel_hi:[1,0]
	v_add_f32_e32 v12, v12, v13
	v_sub_f32_e32 v13, v20, v21
	v_add_f32_e32 v6, v6, v7
	v_sub_f32_e32 v7, v14, v15
	v_add_f32_e32 v10, v10, v11
	v_sub_f32_e32 v11, v22, v23
	v_add_f32_e32 v8, v8, v9
	v_sub_f32_e32 v1, v24, v25
	v_cvt_pk_bf16_f32 v162, v1, v12
	v_cvt_pk_bf16_f32 v163, v13, v6
	v_cvt_pk_bf16_f32 v164, v7, v10
	v_cvt_pk_bf16_f32 v165, v11, v8
	global_load_dwordx4 v[6:9], v[2:3], off offset:288
	global_load_dwordx4 v[10:13], v[4:5], off offset:32
	global_load_dwordx4 v[14:17], v[18:19], off offset:32
	s_waitcnt vmcnt(2)
	v_lshlrev_b32_e32 v20, 16, v6
	s_waitcnt vmcnt(1)
	v_mov_b32_e32 v22, v10
	s_waitcnt vmcnt(0)
	v_mov_b32_e32 v23, v14
	v_mov_b32_e32 v14, v11
	v_mov_b32_e32 v24, v12
	v_mov_b32_e32 v25, v16
	v_mov_b32_e32 v16, v13
	v_and_b32_e32 v21, 0xffff0000, v6
	v_lshlrev_b32_e32 v6, 16, v7
	v_and_b32_e32 v7, 0xffff0000, v7
	v_lshlrev_b32_e32 v10, 16, v8
	v_and_b32_e32 v11, 0xffff0000, v8
	v_lshlrev_b32_e32 v8, 16, v9
	v_and_b32_e32 v9, 0xffff0000, v9
	v_pk_mul_f32 v[12:13], v[22:23], s[6:7] op_sel_hi:[1,0]
	v_pk_mul_f32 v[14:15], v[14:15], s[6:7] op_sel_hi:[1,0]
	v_pk_mul_f32 v[22:23], v[24:25], s[6:7] op_sel_hi:[1,0]
	v_pk_mul_f32 v[16:17], v[16:17], s[6:7] op_sel_hi:[1,0]
	v_pk_mul_f32 v[24:25], v[12:13], v[20:21]
	v_pk_mul_f32 v[12:13], v[12:13], v[20:21] op_sel:[0,1] op_sel_hi:[1,0]
	v_pk_mul_f32 v[20:21], v[14:15], v[6:7]
	v_pk_mul_f32 v[6:7], v[14:15], v[6:7] op_sel:[0,1] op_sel_hi:[1,0]
	v_pk_mul_f32 v[14:15], v[22:23], v[10:11]
	v_pk_mul_f32 v[10:11], v[22:23], v[10:11] op_sel:[0,1] op_sel_hi:[1,0]
	v_pk_mul_f32 v[22:23], v[16:17], v[8:9]
	v_pk_mul_f32 v[8:9], v[16:17], v[8:9] op_sel:[0,1] op_sel_hi:[1,0]
	v_add_f32_e32 v12, v12, v13
	v_sub_f32_e32 v13, v20, v21
	v_add_f32_e32 v6, v6, v7
	v_sub_f32_e32 v7, v14, v15
	v_add_f32_e32 v10, v10, v11
	v_sub_f32_e32 v11, v22, v23
	v_add_f32_e32 v8, v8, v9
	v_sub_f32_e32 v1, v24, v25
	v_cvt_pk_bf16_f32 v166, v1, v12
	v_cvt_pk_bf16_f32 v167, v13, v6
	v_cvt_pk_bf16_f32 v168, v7, v10
	v_cvt_pk_bf16_f32 v169, v11, v8
	global_load_dwordx4 v[6:9], v[2:3], off offset:320
	global_load_dwordx4 v[10:13], v[4:5], off offset:64
	global_load_dwordx4 v[14:17], v[18:19], off offset:64
	s_waitcnt vmcnt(2)
	v_lshlrev_b32_e32 v20, 16, v6
	s_waitcnt vmcnt(1)
	v_mov_b32_e32 v22, v10
	s_waitcnt vmcnt(0)
	v_mov_b32_e32 v23, v14
	v_mov_b32_e32 v14, v11
	v_mov_b32_e32 v24, v12
	v_mov_b32_e32 v25, v16
	v_mov_b32_e32 v16, v13
	v_and_b32_e32 v21, 0xffff0000, v6
	v_lshlrev_b32_e32 v6, 16, v7
	v_and_b32_e32 v7, 0xffff0000, v7
	v_lshlrev_b32_e32 v10, 16, v8
	v_and_b32_e32 v11, 0xffff0000, v8
	v_lshlrev_b32_e32 v8, 16, v9
	v_and_b32_e32 v9, 0xffff0000, v9
	v_pk_mul_f32 v[12:13], v[22:23], s[6:7] op_sel_hi:[1,0]
	v_pk_mul_f32 v[14:15], v[14:15], s[6:7] op_sel_hi:[1,0]
	v_pk_mul_f32 v[22:23], v[24:25], s[6:7] op_sel_hi:[1,0]
	v_pk_mul_f32 v[16:17], v[16:17], s[6:7] op_sel_hi:[1,0]
	v_pk_mul_f32 v[24:25], v[12:13], v[20:21]
	v_pk_mul_f32 v[12:13], v[12:13], v[20:21] op_sel:[0,1] op_sel_hi:[1,0]
	v_pk_mul_f32 v[20:21], v[14:15], v[6:7]
	v_pk_mul_f32 v[6:7], v[14:15], v[6:7] op_sel:[0,1] op_sel_hi:[1,0]
	v_pk_mul_f32 v[14:15], v[22:23], v[10:11]
	v_pk_mul_f32 v[10:11], v[22:23], v[10:11] op_sel:[0,1] op_sel_hi:[1,0]
	v_pk_mul_f32 v[22:23], v[16:17], v[8:9]
	v_pk_mul_f32 v[8:9], v[16:17], v[8:9] op_sel:[0,1] op_sel_hi:[1,0]
	v_sub_f32_e32 v1, v24, v25
	v_add_f32_e32 v12, v12, v13
	v_sub_f32_e32 v13, v20, v21
	v_add_f32_e32 v6, v6, v7
	v_sub_f32_e32 v7, v14, v15
	v_add_f32_e32 v10, v10, v11
	v_sub_f32_e32 v11, v22, v23
	v_add_f32_e32 v8, v8, v9
	v_cvt_pk_bf16_f32 v170, v1, v12
	v_cvt_pk_bf16_f32 v171, v13, v6
	v_cvt_pk_bf16_f32 v172, v7, v10
	v_cvt_pk_bf16_f32 v173, v11, v8
	global_load_dwordx4 v[32:35], v[2:3], off offset:352
	global_load_dwordx4 v[36:39], v[4:5], off offset:96
	global_load_dwordx4 v[40:43], v[18:19], off offset:96
	v_mov_b32_e32 v14, v0
	v_mov_b32_e32 v15, v0
	v_mov_b32_e32 v1, v0
	v_mov_b32_e32 v2, v0
	v_mov_b32_e32 v3, v0
	v_mov_b32_e32 v4, v0
	v_mov_b32_e32 v5, v0
	v_mov_b32_e32 v6, v0
	v_mov_b32_e32 v7, v0
	v_mov_b32_e32 v8, v0
	v_mov_b32_e32 v9, v0
	v_mov_b32_e32 v10, v0
	v_mov_b32_e32 v11, v0
	v_mov_b32_e32 v12, v0
	v_mov_b32_e32 v13, v0
	v_mov_b64_e32 v[30:31], v[14:15]
	v_mov_b64_e32 v[28:29], v[12:13]
	v_mov_b64_e32 v[26:27], v[10:11]
	v_mov_b64_e32 v[24:25], v[8:9]
	v_mov_b64_e32 v[22:23], v[6:7]
	v_mov_b64_e32 v[20:21], v[4:5]
	v_mov_b64_e32 v[18:19], v[2:3]
	v_mov_b64_e32 v[16:17], v[0:1]
	s_waitcnt vmcnt(2)
	v_lshlrev_b32_e32 v44, 16, v32
	s_waitcnt vmcnt(1)
	v_mov_b32_e32 v46, v36
	s_waitcnt vmcnt(0)
; __device__ __forceinline__ float bf2f(unsigned h) { return __uint_as_float(h << 16); }
; #define WAIT_BAR(N) asm volatile("s_waitcnt vmcnt(" #N ") lgkmcnt(0)\n\ts_barrier" ::: "memory")
; #define EXP16(P) do { _Pragma("unroll") for (int r = 0; r < 16; ++r) P[r] = __builtin_amdgcn_exp2f(P[r]); } while (0)
; __device__ __forceinline__ void qkt192n(f32x16& p0, f32x16& p1, const char* Ks, const char* Kr, const bf16x8* qr, const f32x16& negm, int r32, int hi) {
; #pragma unroll
;   for (int d0 = 0; d0 < 8; ++d0) { const int cb = d0 * 32 + hi * 16;
;     const bf16x8 b0 = *reinterpret_cast<const bf16x8*>(Ks + KSWZ(r32, cb));
;     const bf16x8 b1 = *reinterpret_cast<const bf16x8*>(Ks + KSWZ(32 + r32, cb));
;     if (d0 == 0) { p0 = __builtin_amdgcn_mfma_f32_32x32x16_bf16(b0, qr[0], negm, 0, 0, 0); p1 = __builtin_amdgcn_mfma_f32_32x32x16_bf16(b1, qr[0], negm, 0, 0, 0); }
;     else { p0 = __builtin_amdgcn_mfma_f32_32x32x16_bf16(b0, qr[d0], p0, 0, 0, 0); p1 = __builtin_amdgcn_mfma_f32_32x32x16_bf16(b1, qr[d0], p1, 0, 0, 0); } }
; #pragma unroll
;   for (int d0 = 0; d0 < 4; ++d0) { const int cb = d0 * 32 + hi * 16;
;     const bf16x8 b0 = *reinterpret_cast<const bf16x8*>(Kr + RSWZ(r32, cb));
;     const bf16x8 b1 = *reinterpret_cast<const bf16x8*>(Kr + RSWZ(32 + r32, cb));
;     p0 = __builtin_amdgcn_mfma_f32_32x32x16_bf16(b0, qr[8 + d0], p0, 0, 0, 0);
;     p1 = __builtin_amdgcn_mfma_f32_32x32x16_bf16(b1, qr[8 + d0], p1, 0, 0, 0); }
; __device__ __forceinline__ void mla_unit(char* lds, const bf16_t* __restrict__ Qp, const bf16_t* __restrict__ Knp, const bf16_t* __restrict__ Vp, ...
;     ...
;       const u32x4 raw = *reinterpret_cast<const u32x4*>(Qw + 128 + d0 * 16);
;       const int i0 = d0 * 8 + hi * 4;
;       const f32x4 cc = *reinterpret_cast<const f32x4*>(cs_tab + pos * 32 + i0) * C, ss = *reinterpret_cast<const f32x4*>(sn_tab + pos * 32 + i0) * C;
;       u32x4 w;
; #pragma unroll
;       for (int p = 0; p < 4; ++p) { const float x1 = bf2f(raw[p] & 0xffffu), x2 = bf2f(raw[p] >> 16); w[p] = cvtpk(x1 * cc[p] - x2 * ss[p], x1 * ss[p] + x2 * cc[p]); }
;       qr[8 + d0] = *reinterpret_cast<bf16x8*>(&w);
;     } }
;     ...
;   WAIT_BAR(10);
;   qkt192n(pA0, pA1, (const char*)lds + P_KN, (const char*)lds + P_KR, qr, negm, r32, hi); NEWMAX(pA0, pA1, true); EXP16(pA0); HALF0(pA0);
	v_mov_b32_e32 v47, v40
	v_mov_b32_e32 v40, v37
	v_mov_b32_e32 v52, v38
	v_mov_b32_e32 v53, v42
	v_mov_b32_e32 v42, v39
	v_and_b32_e32 v45, 0xffff0000, v32
	v_lshlrev_b32_e32 v32, 16, v33
	v_and_b32_e32 v33, 0xffff0000, v33
	v_lshlrev_b32_e32 v36, 16, v34
	v_and_b32_e32 v37, 0xffff0000, v34
	v_lshlrev_b32_e32 v34, 16, v35
	v_and_b32_e32 v35, 0xffff0000, v35
	v_pk_mul_f32 v[38:39], v[46:47], s[6:7] op_sel_hi:[1,0]
	v_pk_mul_f32 v[40:41], v[40:41], s[6:7] op_sel_hi:[1,0]
	v_pk_mul_f32 v[46:47], v[52:53], s[6:7] op_sel_hi:[1,0]
	v_pk_mul_f32 v[42:43], v[42:43], s[6:7] op_sel_hi:[1,0]
	v_pk_mul_f32 v[52:53], v[38:39], v[44:45]
	v_pk_mul_f32 v[38:39], v[38:39], v[44:45] op_sel:[0,1] op_sel_hi:[1,0]
	v_pk_mul_f32 v[44:45], v[40:41], v[32:33]
	v_pk_mul_f32 v[32:33], v[40:41], v[32:33] op_sel:[0,1] op_sel_hi:[1,0]
	v_pk_mul_f32 v[40:41], v[46:47], v[36:37]
	v_pk_mul_f32 v[36:37], v[46:47], v[36:37] op_sel:[0,1] op_sel_hi:[1,0]
	v_pk_mul_f32 v[46:47], v[42:43], v[34:35]
	v_pk_mul_f32 v[34:35], v[42:43], v[34:35] op_sel:[0,1] op_sel_hi:[1,0]
	v_sub_f32_e32 v42, v52, v53
	v_add_f32_e32 v38, v38, v39
	v_sub_f32_e32 v39, v44, v45
	v_add_f32_e32 v32, v32, v33
	v_sub_f32_e32 v33, v40, v41
	v_add_f32_e32 v36, v36, v37
	v_sub_f32_e32 v37, v46, v47
	v_add_f32_e32 v34, v34, v35
	v_cvt_pk_bf16_f32 v174, v42, v38
	v_cvt_pk_bf16_f32 v175, v39, v32
	v_cvt_pk_bf16_f32 v176, v33, v36
	v_cvt_pk_bf16_f32 v177, v37, v34
	s_waitcnt vmcnt(10) lgkmcnt(0)
	s_barrier
	ds_read_b128 v[52:55], v56 offset:49152
	ds_read_b128 v[56:59], v56 offset:57344
	s_waitcnt lgkmcnt(1)
	v_mfma_f32_32x32x16_bf16 v[32:47], v[52:55], v[130:133], v[16:31]
	v_or_b32_e32 v52, 32, v194
	v_xad_u32 v53, v52, v51, v66
	s_waitcnt lgkmcnt(0)
	v_mfma_f32_32x32x16_bf16 v[16:31], v[56:59], v[130:133], v[16:31]
	ds_read_b128 v[54:57], v53 offset:49152
	ds_read_b128 v[58:61], v53 offset:57344
	v_or_b32_e32 v53, 64, v194
	v_xad_u32 v62, v53, v51, v66
	s_waitcnt lgkmcnt(1)
	v_mfma_f32_32x32x16_bf16 v[32:47], v[54:57], v[134:137], v[32:47]
	s_waitcnt lgkmcnt(0)
	v_mfma_f32_32x32x16_bf16 v[16:31], v[58:61], v[134:137], v[16:31]
	ds_read_b128 v[54:57], v62 offset:49152
	ds_read_b128 v[58:61], v62 offset:57344
	s_waitcnt lgkmcnt(1)
	v_mfma_f32_32x32x16_bf16 v[32:47], v[54:57], v[138:141], v[32:47]
	v_or_b32_e32 v54, 0x60, v194
	v_xad_u32 v55, v54, v51, v66
	s_waitcnt lgkmcnt(0)
	v_mfma_f32_32x32x16_bf16 v[16:31], v[58:61], v[138:141], v[16:31]
	ds_read_b128 v[56:59], v55 offset:49152
	ds_read_b128 v[60:63], v55 offset:57344
	v_or_b32_e32 v55, 0x80, v194
	v_xad_u32 v64, v55, v51, v66
	s_waitcnt lgkmcnt(1)
	v_mfma_f32_32x32x16_bf16 v[32:47], v[56:59], v[142:145], v[32:47]
	s_waitcnt lgkmcnt(0)
	v_mfma_f32_32x32x16_bf16 v[16:31], v[60:63], v[142:145], v[16:31]
	ds_read_b128 v[56:59], v64 offset:49152
	ds_read_b128 v[60:63], v64 offset:57344
	s_waitcnt lgkmcnt(1)
	v_mfma_f32_32x32x16_bf16 v[32:47], v[56:59], v[154:157], v[32:47]
	v_or_b32_e32 v56, 0xa0, v194
	v_xad_u32 v57, v56, v51, v66
	s_waitcnt lgkmcnt(0)
	v_mfma_f32_32x32x16_bf16 v[16:31], v[60:63], v[154:157], v[16:31]
	ds_read_b128 v[58:61], v57 offset:49152
	ds_read_b128 v[62:65], v57 offset:57344
	v_or_b32_e32 v57, 0xc0, v194
	v_xad_u32 v67, v57, v51, v66
	s_waitcnt lgkmcnt(1)
	v_mfma_f32_32x32x16_bf16 v[32:47], v[58:61], v[150:153], v[32:47]
	s_waitcnt lgkmcnt(0)
	v_mfma_f32_32x32x16_bf16 v[16:31], v[62:65], v[150:153], v[16:31]
	ds_read_b128 v[58:61], v67 offset:49152
	ds_read_b128 v[62:65], v67 offset:57344
	s_waitcnt lgkmcnt(1)
	v_mfma_f32_32x32x16_bf16 v[32:47], v[58:61], v[146:149], v[32:47]
	v_or_b32_e32 v58, 0xe0, v194
	v_xad_u32 v59, v58, v51, v66
	s_waitcnt lgkmcnt(0)
	v_mfma_f32_32x32x16_bf16 v[16:31], v[62:65], v[146:149], v[16:31]
	ds_read_b128 v[60:63], v59 offset:49152
	ds_read_b128 v[64:67], v59 offset:57344
	v_lshlrev_b32_e32 v59, 3, v50
	v_and_b32_e32 v68, 0x70, v59
	v_xad_u32 v69, v194, v68, v206
	v_and_b32_e32 v50, 63, v50
	v_cmp_gt_u32_e64 s[40:41], 32, v50
	s_waitcnt lgkmcnt(1)
	v_mfma_f32_32x32x16_bf16 v[32:47], v[60:63], v[158:161], v[32:47]
	s_waitcnt lgkmcnt(0)
	v_mfma_f32_32x32x16_bf16 v[16:31], v[64:67], v[158:161], v[16:31]
	ds_read_b128 v[60:63], v69
	ds_read_b128 v[64:67], v69 offset:4096
	v_xad_u32 v69, v52, v68, v206
	s_waitcnt lgkmcnt(1)
	v_mfma_f32_32x32x16_bf16 v[32:47], v[60:63], v[162:165], v[32:47]
	s_waitcnt lgkmcnt(0)
	v_mfma_f32_32x32x16_bf16 v[16:31], v[64:67], v[162:165], v[16:31]
	ds_read_b128 v[60:63], v69
	ds_read_b128 v[64:67], v69 offset:4096
	v_xad_u32 v69, v53, v68, v206
	v_xad_u32 v68, v54, v68, v206
	s_waitcnt lgkmcnt(1)
	v_mfma_f32_32x32x16_bf16 v[32:47], v[60:63], v[166:169], v[32:47]
	s_waitcnt lgkmcnt(0)
	v_mfma_f32_32x32x16_bf16 v[16:31], v[64:67], v[166:169], v[16:31]
	ds_read_b128 v[60:63], v69
	ds_read_b128 v[64:67], v69 offset:4096
	s_waitcnt lgkmcnt(1)
	v_mfma_f32_32x32x16_bf16 v[32:47], v[60:63], v[170:173], v[32:47]
	s_waitcnt lgkmcnt(0)
	v_mfma_f32_32x32x16_bf16 v[16:31], v[64:67], v[170:173], v[16:31]
	ds_read_b128 v[60:63], v68
	ds_read_b128 v[64:67], v68 offset:4096
	s_waitcnt lgkmcnt(1)
	v_mfma_f32_32x32x16_bf16 v[32:47], v[60:63], v[174:177], v[32:47]
	s_waitcnt lgkmcnt(0)
; #define WAIT_BAR(N) asm volatile("s_waitcnt vmcnt(" #N ") lgkmcnt(0)\n\ts_barrier" ::: "memory")
; #define EXP16(P) do { _Pragma("unroll") for (int r = 0; r < 16; ++r) P[r] = __builtin_amdgcn_exp2f(P[r]); } while (0)
; #define EXP16(P) do { _Pragma("unroll") for (int r = 0; r < 16; ++r) P[r] = __builtin_amdgcn_exp2f(P[r]); } while (0)
; __device__ __forceinline__ void mla_unit(char* lds, const bf16_t* __restrict__ Qp, const bf16_t* __restrict__ Knp, const bf16_t* __restrict__ Vp, ...
;     ...
;   bool resc = false; float sum0 = 0.f;
;     ...
;   WAIT_BAR(10);
;   qkt192n(pA0, pA1, (const char*)lds + P_KN, (const char*)lds + P_KR, qr, negm, r32, hi); NEWMAX(pA0, pA1, true); EXP16(pA0); HALF0(pA0);
;   int s0 = 0, s1 = 1, s2 = 2;
	v_mfma_f32_32x32x16_bf16 v[16:31], v[64:67], v[174:177], v[16:31]
	s_nop 9
	v_max_f32_e32 v60, v33, v33
	v_max_f32_e32 v61, v32, v32
	v_max_f32_e32 v60, v61, v60
	v_max3_f32 v62, v34, v35, v17
	v_max3_f32 v60, v60, v16, v18
	v_max3_f32 v61, v62, v38, v39
	v_max3_f32 v60, v60, v19, v36
	v_max3_f32 v61, v61, v22, v23
	v_max3_f32 v60, v60, v37, v20
	v_max3_f32 v61, v61, v42, v43
	v_max3_f32 v60, v60, v21, v40
	v_max3_f32 v61, v61, v26, v27
	v_max3_f32 v60, v60, v41, v24
	v_max3_f32 v61, v61, v46, v47
	v_max3_f32 v60, v60, v25, v44
	v_max3_f32 v61, v61, v30, v31
	v_max3_f32 v60, v60, v45, v28
	v_max3_f32 v60, v60, v29, v61
	v_mov_b32_e32 v61, v60
	s_nop 1
	v_permlane32_swap_b32_e32 v60, v61
	v_max_f32_e32 v61, v61, v61
	v_max_f32_e32 v60, v60, v60
	v_max_f32_e32 v61, v60, v61
	v_exp_f32_e64 v60, -v61
	v_add_f32_e32 v203, 0, v61
	v_xor_b32_e32 v66, 0x80000000, v203
	v_mov_b32_e32 v67, v66
	v_mov_b32_e32 v68, v66
	v_mov_b32_e32 v69, v66
	v_mov_b32_e32 v70, v66
	v_mov_b32_e32 v71, v66
	v_mov_b32_e32 v72, v66
	v_mov_b32_e32 v73, v66
	v_mov_b32_e32 v74, v66
	v_mov_b32_e32 v75, v66
	v_mov_b32_e32 v76, v66
	v_mov_b32_e32 v77, v66
	v_mov_b32_e32 v78, v66
	v_mov_b32_e32 v79, v66
	v_mov_b32_e32 v80, v66
	v_mov_b32_e32 v81, v66
	s_and_saveexec_b64 s[6:7], s[40:41]
	ds_write_b32 v200, v60 offset:128
	s_or_b64 exec, exec, s[6:7]
	v_sub_f32_e32 v32, v32, v61
	v_sub_f32_e32 v33, v33, v61
	v_sub_f32_e32 v82, v16, v61
	v_exp_f32_e32 v16, v32
	v_sub_f32_e32 v34, v34, v61
	v_sub_f32_e32 v83, v17, v61
	v_exp_f32_e32 v17, v33
	v_sub_f32_e32 v35, v35, v61
	v_sub_f32_e32 v84, v18, v61
	v_exp_f32_e32 v18, v34
	v_sub_f32_e32 v36, v36, v61
	v_sub_f32_e32 v85, v19, v61
	v_exp_f32_e32 v19, v35
	v_sub_f32_e32 v37, v37, v61
	v_sub_f32_e32 v86, v20, v61
	v_exp_f32_e32 v20, v36
	v_add_f32_e32 v32, 0, v16
	v_sub_f32_e32 v38, v38, v61
	v_sub_f32_e32 v87, v21, v61
	v_exp_f32_e32 v21, v37
	v_add_f32_e32 v32, v17, v32
	v_sub_f32_e32 v39, v39, v61
	v_sub_f32_e32 v88, v22, v61
	v_exp_f32_e32 v22, v38
	v_add_f32_e32 v32, v18, v32
	v_sub_f32_e32 v40, v40, v61
	v_sub_f32_e32 v89, v23, v61
	v_exp_f32_e32 v23, v39
	v_add_f32_e32 v32, v19, v32
	v_sub_f32_e32 v41, v41, v61
	v_sub_f32_e32 v90, v24, v61
	v_exp_f32_e32 v24, v40
	v_add_f32_e32 v32, v20, v32
	v_sub_f32_e32 v42, v42, v61
	v_sub_f32_e32 v91, v25, v61
	v_exp_f32_e32 v25, v41
	v_add_f32_e32 v32, v21, v32
	v_sub_f32_e32 v43, v43, v61
	v_sub_f32_e32 v92, v26, v61
	v_exp_f32_e32 v26, v42
	v_add_f32_e32 v32, v22, v32
	v_sub_f32_e32 v44, v44, v61
	v_sub_f32_e32 v93, v27, v61
	v_exp_f32_e32 v27, v43
	v_add_f32_e32 v32, v23, v32
	v_sub_f32_e32 v45, v45, v61
	v_sub_f32_e32 v94, v28, v61
	v_exp_f32_e32 v28, v44
	v_add_f32_e32 v32, v24, v32
	s_lshr_b32 s69, s74, 5
	v_sub_f32_e32 v46, v46, v61
	v_sub_f32_e32 v95, v29, v61
	v_exp_f32_e32 v29, v45
	v_add_f32_e32 v32, v25, v32
	v_sub_f32_e32 v47, v47, v61
	v_sub_f32_e32 v96, v30, v61
	s_and_b32 s0, s69, 15
	v_exp_f32_e32 v30, v46
	v_add_f32_e32 v32, v26, v32
	s_movk_i32 s1, 0x70
	v_sub_f32_e32 v97, v31, v61
	s_lshl_b32 s0, s0, 23
	v_exp_f32_e32 v31, v47
	v_add_f32_e32 v32, v27, v32
	v_bitop3_b32 v221, v194, v59, s1 bitop3:0x78
	v_bitop3_b32 v209, v52, v59, s1 bitop3:0x78
	v_bitop3_b32 v208, v53, v59, s1 bitop3:0x78
	v_bitop3_b32 v207, v54, v59, s1 bitop3:0x78
	v_readlane_b32 s1, v254, 9
	v_lshlrev_b32_e32 v62, 4, v50
	v_add_f32_e32 v32, v28, v32
	s_add_u32 s36, s1, s36
	v_readlane_b32 s1, v254, 10
	v_lshlrev_b32_e32 v195, 2, v49
	v_lshlrev_b32_e32 v49, 3, v50
	v_and_b32_e32 v62, 0xc0, v62
	v_lshlrev_b32_e32 v50, 1, v50
	v_add_f32_e32 v32, v29, v32
	s_addc_u32 s37, s1, s37
	v_and_or_b32 v62, v49, 24, v62
	v_and_b32_e32 v50, 32, v50
	v_and_b32_e32 v49, 0x100, v49
	v_add_f32_e32 v32, v30, v32
	s_add_u32 s0, s0, s30
	v_or3_b32 v201, v62, v50, v49
	v_mul_f32_e32 v234, 0, v60
	v_add_f32_e32 v186, v31, v32
	v_cvt_pk_bf16_f32 v182, v16, v17
	v_cvt_pk_bf16_f32 v183, v18, v19
	v_cvt_pk_bf16_f32 v184, v20, v21
	v_cvt_pk_bf16_f32 v185, v22, v23
	v_cvt_pk_bf16_f32 v178, v24, v25
	v_cvt_pk_bf16_f32 v179, v26, v27
	v_cvt_pk_bf16_f32 v180, v28, v29
	v_cvt_pk_bf16_f32 v181, v30, v31
	v_bitop3_b32 v229, v194, v48, s53 bitop3:0x78
	v_bitop3_b32 v230, v194, v204, v51 bitop3:0xde
	v_bitop3_b32 v228, v52, v48, s53 bitop3:0x78
	v_bitop3_b32 v231, v52, v204, v51 bitop3:0xde
	v_bitop3_b32 v227, v53, v48, s53 bitop3:0x78
	v_bitop3_b32 v226, v54, v48, s53 bitop3:0x78
	v_bitop3_b32 v225, v55, v48, s53 bitop3:0x78
	v_bitop3_b32 v224, v56, v48, s53 bitop3:0x78
	v_bitop3_b32 v223, v57, v48, s53 bitop3:0x78
	v_bitop3_b32 v222, v58, v48, s53 bitop3:0x78
	s_addc_u32 s1, 0, s31
	v_readlane_b32 s12, v254, 35
	v_mov_b64_e32 v[64:65], v[14:15]
	v_mov_b64_e32 v[48:49], v[14:15]
	v_mov_b64_e32 v[32:33], v[14:15]
	v_readlane_b32 s13, v254, 36
	s_add_u32 s30, s12, s0
	v_mov_b64_e32 v[62:63], v[12:13]
	v_mov_b64_e32 v[60:61], v[10:11]
	v_mov_b64_e32 v[58:59], v[8:9]
	v_mov_b64_e32 v[56:57], v[6:7]
	v_mov_b64_e32 v[54:55], v[4:5]
	v_mov_b64_e32 v[52:53], v[2:3]
	v_mov_b64_e32 v[50:51], v[0:1]
	v_mov_b64_e32 v[46:47], v[12:13]
	v_mov_b64_e32 v[44:45], v[10:11]
	v_mov_b64_e32 v[42:43], v[8:9]
	v_mov_b64_e32 v[40:41], v[6:7]
	v_mov_b64_e32 v[38:39], v[4:5]
	v_mov_b64_e32 v[36:37], v[2:3]
	v_mov_b64_e32 v[34:35], v[0:1]
	v_mov_b64_e32 v[30:31], v[12:13]
	v_mov_b64_e32 v[28:29], v[10:11]
	v_mov_b64_e32 v[26:27], v[8:9]
	v_mov_b64_e32 v[24:25], v[6:7]
	v_mov_b64_e32 v[22:23], v[4:5]
	v_mov_b64_e32 v[20:21], v[2:3]
	v_mov_b64_e32 v[18:19], v[0:1]
	v_mov_b64_e32 v[16:17], v[14:15]
	s_mov_b32 s70, 1
	v_add_u32_e32 v202, 0, v201
	v_permlane32_swap_b32_e32 v182, v184
	v_permlane32_swap_b32_e32 v183, v185
	v_permlane32_swap_b32_e32 v178, v180
	v_permlane32_swap_b32_e32 v179, v181
	s_mov_b32 s77, 2
	v_add_u32_e32 v232, v229, v204
	v_add_u32_e32 v233, v228, v204
	s_addc_u32 s31, s13, s1
	s_mov_b32 s78, 0
	v_mov_b64_e32 v[14:15], v[12:13]
	v_mov_b64_e32 v[12:13], v[10:11]
	v_mov_b64_e32 v[10:11], v[8:9]
	v_mov_b64_e32 v[8:9], v[6:7]
	v_mov_b64_e32 v[6:7], v[4:5]
	v_mov_b64_e32 v[4:5], v[2:3]
	v_mov_b64_e32 v[2:3], v[0:1]
	s_mov_b32 s0, 0
	v_readlane_b32 s14, v254, 37
	v_readlane_b32 s15, v254, 38
	s_cmp_eq_u32 s100, 0
	s_cbranch_scc1 .Lmla_noX
	s_waitcnt vmcnt(5) lgkmcnt(0)
	s_barrier
.Lmla_noX:
.LBB0_241:
	s_waitcnt vmcnt(5) lgkmcnt(0)
	s_barrier
	s_mov_b32 s79, s70
	s_mov_b32 s70, s0
	s_lshl_b32 s13, s79, 14
	s_lshl_b32 s0, s79, 13
	s_lshl_b32 s1, s70, 14
	s_add_i32 s5, s13, 0
	v_add_u32_e32 v1, s5, v230
	v_add_u32_e32 v102, s5, v232
	ds_read_b128 v[98:101], v1 offset:49152
	ds_read_b128 v[236:239], v102 offset:57344
	v_add_u32_e32 v1, s5, v231
	v_add_u32_e32 v102, s5, v233
	ds_read_b128 v[240:243], v1 offset:49152
	ds_read_b128 v[244:247], v102 offset:57344
	s_waitcnt lgkmcnt(3)
	v_mfma_f32_32x32x16_bf16 v[114:129], v[98:101], v[130:133], v[66:81]
	v_add_u32_e32 v1, s5, v204
	v_add_u32_e32 v102, v1, v227
	ds_read_b128 v[248:251], v102 offset:49152
	v_add_u32_e32 v190, s1, v202
	v_add_u32_e32 v191, s0, v206
	v_exp_f32_e32 v192, v82
	ds_read_b128 v[210:213], v102 offset:57344
	s_waitcnt lgkmcnt(4)
	v_mfma_f32_32x32x16_bf16 v[98:113], v[236:239], v[130:133], v[66:81]
	v_add_f32_e32 v82, v192, v186
	v_exp_f32_e32 v193, v83
	s_waitcnt lgkmcnt(3)
	v_mfma_f32_32x32x16_bf16 v[114:129], v[240:243], v[134:137], v[114:129]
	v_add_u32_e32 v83, v1, v226
	ds_read_b128 v[186:189], v83 offset:49152
	v_add_f32_e32 v82, v193, v82
	v_exp_f32_e32 v235, v84
	s_waitcnt lgkmcnt(3)
	v_mfma_f32_32x32x16_bf16 v[98:113], v[244:247], v[134:137], v[98:113]
	ds_read_b128 v[236:239], v83 offset:57344
	v_add_f32_e32 v240, v235, v82
	v_exp_f32_e32 v220, v85
	s_waitcnt lgkmcnt(3)
	v_mfma_f32_32x32x16_bf16 v[114:129], v[248:251], v[138:141], v[114:129]
	v_add_u32_e32 v241, v1, v225
	ds_read_b128 v[82:85], v241 offset:49152
	v_exp_f32_e32 v244, v86
	v_add_f32_e32 v86, v220, v240
	s_waitcnt lgkmcnt(3)
	v_mfma_f32_32x32x16_bf16 v[98:113], v[210:213], v[138:141], v[98:113]
	ds_read_b128 v[240:243], v241 offset:57344
	v_add_f32_e32 v86, v244, v86
	v_exp_f32_e32 v245, v87
	s_waitcnt lgkmcnt(3)
	v_mfma_f32_32x32x16_bf16 v[114:129], v[186:189], v[142:145], v[114:129]
	v_add_u32_e32 v87, v1, v224
	ds_read_b128 v[210:213], v87 offset:49152
	v_add_f32_e32 v86, v245, v86
	v_exp_f32_e32 v246, v88
	s_waitcnt lgkmcnt(3)
	v_mfma_f32_32x32x16_bf16 v[98:113], v[236:239], v[142:145], v[98:113]
	ds_read_b128 v[186:189], v87 offset:57344
	v_add_f32_e32 v248, v246, v86
	v_exp_f32_e32 v247, v89
	s_waitcnt lgkmcnt(3)
	v_mfma_f32_32x32x16_bf16 v[114:129], v[82:85], v[154:157], v[114:129]
	v_add_u32_e32 v236, v1, v223
	ds_read_b128 v[86:89], v236 offset:49152
	v_add_f32_e32 v82, v247, v248
	v_exp_f32_e32 v249, v90
	s_waitcnt lgkmcnt(3)
	v_mfma_f32_32x32x16_bf16 v[98:113], v[240:243], v[154:157], v[98:113]
	ds_read_b128 v[236:239], v236 offset:57344
	v_add_f32_e32 v84, v249, v82
	v_exp_f32_e32 v248, v91
	v_cvt_pk_bf16_f32 v82, v192, v193
	v_cvt_pk_bf16_f32 v83, v235, v220
	s_waitcnt lgkmcnt(3)
	v_mfma_f32_32x32x16_bf16 v[114:129], v[210:213], v[150:153], v[114:129]
	v_add_u32_e32 v1, v1, v222
	ds_read_b128 v[240:243], v1 offset:49152
	v_add_f32_e32 v90, v248, v84
	v_exp_f32_e32 v192, v92
	v_cvt_pk_bf16_f32 v84, v244, v245
	v_cvt_pk_bf16_f32 v85, v246, v247
	s_waitcnt lgkmcnt(3)
	v_mfma_f32_32x32x16_bf16 v[98:113], v[186:189], v[150:153], v[98:113]
	ds_read_b128 v[210:213], v1 offset:57344
	v_exp_f32_e32 v1, v93
	v_add_f32_e32 v193, v192, v90
	v_permlane32_swap_b32_e32 v82, v84
	v_permlane32_swap_b32_e32 v83, v85
	s_waitcnt lgkmcnt(3)
	v_mfma_f32_32x32x16_bf16 v[114:129], v[86:89], v[146:149], v[114:129]
	v_add_u32_e32 v186, v191, v221
	ds_read_b128 v[90:93], v186
	v_exp_f32_e32 v220, v94
	v_add_f32_e32 v94, v1, v193
	s_waitcnt lgkmcnt(3)
	v_mfma_f32_32x32x16_bf16 v[98:113], v[236:239], v[146:149], v[98:113]
	ds_read_b128 v[86:89], v186 offset:4096
	v_add_f32_e32 v94, v220, v94
	v_exp_f32_e32 v193, v95
	s_waitcnt lgkmcnt(3)
	v_mfma_f32_32x32x16_bf16 v[114:129], v[240:243], v[158:161], v[114:129]
	v_add_u32_e32 v95, v191, v209
	ds_read_b128 v[186:189], v95
	v_add_f32_e32 v94, v193, v94
	v_exp_f32_e32 v235, v96
	s_waitcnt lgkmcnt(3)
	v_mfma_f32_32x32x16_bf16 v[98:113], v[210:213], v[158:161], v[98:113]
	ds_read_b128 v[236:239], v95 offset:4096
	v_add_f32_e32 v241, v235, v94
	v_exp_f32_e32 v240, v97
	s_waitcnt lgkmcnt(3)
	v_mfma_f32_32x32x16_bf16 v[114:129], v[90:93], v[162:165], v[114:129]
	v_add_u32_e32 v210, v191, v208
	ds_read_b128 v[94:97], v210
	v_add_f32_e32 v241, v240, v241
	s_waitcnt lgkmcnt(3)
	v_mfma_f32_32x32x16_bf16 v[98:113], v[86:89], v[162:165], v[98:113]
	ds_read_b128 v[90:93], v210 offset:4096
	v_cvt_pk_bf16_f32 v86, v249, v248
	v_cvt_pk_bf16_f32 v87, v192, v1
	s_waitcnt lgkmcnt(3)
	v_mfma_f32_32x32x16_bf16 v[114:129], v[186:189], v[166:169], v[114:129]
	v_add_u32_e32 v1, v191, v207
	ds_read_b128 v[210:213], v1
	v_cvt_pk_bf16_f32 v88, v220, v193
	v_cvt_pk_bf16_f32 v89, v235, v240
	s_waitcnt lgkmcnt(3)
	v_mfma_f32_32x32x16_bf16 v[98:113], v[236:239], v[166:169], v[98:113]
	ds_read_b128 v[186:189], v1 offset:4096
	v_permlane32_swap_b32_e32 v86, v88
	v_permlane32_swap_b32_e32 v87, v89
	s_waitcnt lgkmcnt(3)
	v_mfma_f32_32x32x16_bf16 v[114:129], v[94:97], v[170:173], v[114:129]
	v_mov_b32_e32 v1, v241
	s_nop 1
	v_permlane32_swap_b32_e32 v241, v1
	v_add_f32_e32 v1, v241, v1
	v_add_f32_e32 v1, v234, v1
	s_waitcnt lgkmcnt(2)
	v_mfma_f32_32x32x16_bf16 v[98:113], v[90:93], v[170:173], v[98:113]
	ds_read_b64_tr_b16 v[94:95], v190
	ds_read_b64_tr_b16 v[96:97], v190 offset:2048
	s_waitcnt lgkmcnt(3)
	v_mfma_f32_32x32x16_bf16 v[114:129], v[210:213], v[174:177], v[114:129]
	ds_read_b64_tr_b16 v[90:91], v190 offset:512
	ds_read_b64_tr_b16 v[92:93], v190 offset:2560
	s_waitcnt lgkmcnt(4)
	v_mfma_f32_32x32x16_bf16 v[98:113], v[186:189], v[174:177], v[98:113]
	ds_read_b64_tr_b16 v[210:211], v190 offset:1024
	ds_read_b64_tr_b16 v[212:213], v190 offset:3072
	s_cmp_eq_u32 s100, 0
	s_cbranch_scc1 .Lmla_wbb1
	s_waitcnt vmcnt(0)
; #define MX3(a, b, c) __builtin_fmaxf(__builtin_fmaxf((a), (b)), (c))
; #define MX3(a, b, c) __builtin_fmaxf(__builtin_fmaxf((a), (b)), (c))
; __device__ __forceinline__ float rowmax32(const f32x16& p0, const f32x16& p1) {
;   float a = MX3(p0[0], p0[1], p1[0]), b = MX3(p0[2], p0[3], p1[1]); a = MX3(a, p1[2], p1[3]);
; #pragma unroll
;   for (int r = 4; r < 16; r += 4) { a = MX3(a, p0[r], p0[r + 1]); b = MX3(b, p0[r + 2], p0[r + 3]); a = MX3(a, p1[r], p1[r + 1]); b = MX3(b, p1[r + 2], p1[r + 3]); }
;   float m = __builtin_fmaxf(a, b);
;   auto rr = __builtin_amdgcn_permlane32_swap(__float_as_uint(m), __float_as_uint(m), false, false);
;   return __builtin_fmaxf(__uint_as_float(rr[0]), __uint_as_float(rr[1]));
; }
.Lmla_wbb1:
	s_barrier
	s_add_u32 s18, s30, s46
	s_addc_u32 s19, s31, s47
	s_add_u32 s14, s18, 0x15000000
	s_addc_u32 s15, s19, 0
	s_waitcnt lgkmcnt(4)
	v_mfma_f32_32x32x16_bf16 v[50:65], v[182:185], v[94:97], v[50:65]
	s_add_u32 s6, s18, 0x15018000
	s_addc_u32 s7, s19, 0
	s_add_i32 s5, s1, s76
	s_add_u32 s8, s18, 0x15010100
	ds_read_b64_tr_b16 v[234:235], v190 offset:1536
	ds_read_b64_tr_b16 v[236:237], v190 offset:3584
	s_addc_u32 s9, s19, 0
	s_lshl_b32 s20, s77, 14
	s_add_i32 s12, s20, s73
	s_mov_b32 s16, m0
	s_mov_b32 m0, s12
	s_nop 0
	global_load_lds_dwordx4 v199, s[8:9]
	s_mov_b32 m0, s16
	s_waitcnt lgkmcnt(4)
	v_mfma_f32_32x32x16_bf16 v[34:49], v[182:185], v[90:93], v[34:49]
	ds_read_b64_tr_b16 v[94:95], v190 offset:4096
	ds_read_b64_tr_b16 v[96:97], v190 offset:6144
	s_add_u32 s8, s18, 0x15014100
	s_addc_u32 s9, s19, 0
	s_addk_i32 s12, 0x2000
	s_mov_b32 s16, m0
	s_mov_b32 m0, s12
	s_nop 0
	global_load_lds_dwordx4 v199, s[8:9]
	s_mov_b32 m0, s16
	s_waitcnt lgkmcnt(4)
	v_mfma_f32_32x32x16_bf16 v[18:33], v[182:185], v[210:213], v[18:33]
	ds_read_b64_tr_b16 v[186:187], v190 offset:4608
	ds_read_b64_tr_b16 v[188:189], v190 offset:6656
	s_mov_b32 s8, m0
	s_mov_b32 m0, s5
	s_nop 0
	global_load_lds_dwordx4 v197, s[6:7]
	s_mov_b32 m0, s8
	s_waitcnt lgkmcnt(4)
	v_mfma_f32_32x32x16_bf16 v[2:17], v[182:185], v[234:237], v[2:17]
	ds_read_b64_tr_b16 v[90:91], v190 offset:5120
	ds_read_b64_tr_b16 v[92:93], v190 offset:7168
	s_add_u32 s6, s18, 0x1501a000
	s_addc_u32 s7, s19, 0
	s_addk_i32 s5, 0x1000
	s_mov_b32 s8, m0
	s_mov_b32 m0, s5
	s_nop 0
	global_load_lds_dwordx4 v197, s[6:7]
	s_mov_b32 m0, s8
	v_max_f32_e32 v182, v115, v115
	v_max_f32_e32 v183, v114, v114
	v_max_f32_e32 v182, v183, v182
	v_max3_f32 v183, v116, v117, v99
	v_max3_f32 v182, v182, v98, v100
	v_max3_f32 v182, v182, v101, v118
	v_max3_f32 v183, v183, v120, v121
	v_max3_f32 v182, v182, v119, v102
	v_max3_f32 v183, v183, v104, v105
	v_max3_f32 v182, v182, v103, v122
	v_max3_f32 v183, v183, v124, v125
	v_max3_f32 v182, v182, v123, v106
	v_max3_f32 v183, v183, v108, v109
	v_max3_f32 v182, v182, v107, v126
	v_max3_f32 v183, v183, v128, v129
	v_max3_f32 v182, v182, v127, v110
	v_max3_f32 v183, v183, v112, v113
	v_max3_f32 v182, v182, v111, v183
	v_mov_b32_e32 v183, v182
	s_nop 1
	v_permlane32_swap_b32_e32 v182, v183
	v_max_f32_e32 v183, v183, v183
	v_max_f32_e32 v182, v182, v182
	v_max_f32_e32 v182, v182, v183
	v_cmp_lt_f32_e32 vcc, s92, v182
	s_cmp_lg_u64 vcc, 0
	s_cselect_b64 s[6:7], -1, 0
	s_cbranch_vccnz .LBB0_255

.LBB0_244:
	s_waitcnt vmcnt(5) lgkmcnt(0)
	s_barrier
	s_add_i32 s5, s20, 0
	v_add_u32_e32 v83, s5, v230
	v_add_u32_e32 v88, s5, v232
	ds_read_b128 v[84:87], v83 offset:49152
	ds_read_b128 v[186:189], v88 offset:57344
	v_add_u32_e32 v83, s5, v231
	v_add_u32_e32 v88, s5, v233
	ds_read_b128 v[190:193], v83 offset:49152
	ds_read_b128 v[210:213], v88 offset:57344
	s_waitcnt lgkmcnt(3)
	v_mfma_f32_32x32x16_bf16 v[114:129], v[84:87], v[130:133], v[66:81]
	v_add_u32_e32 v220, s5, v204
	v_add_u32_e32 v83, v220, v227
	ds_read_b128 v[236:239], v83 offset:49152
	v_lshl_add_u32 v234, s77, 13, v206
	v_add_u32_e32 v235, s13, v202
	v_exp_f32_e32 v244, v98
	ds_read_b128 v[240:243], v83 offset:57344
	v_add_f32_e32 v98, v244, v82
	s_waitcnt lgkmcnt(4)
	v_mfma_f32_32x32x16_bf16 v[82:97], v[186:189], v[130:133], v[66:81]
	v_exp_f32_e32 v245, v99
	s_waitcnt lgkmcnt(3)
	v_mfma_f32_32x32x16_bf16 v[114:129], v[190:193], v[134:137], v[114:129]
	v_add_u32_e32 v99, v220, v226
	ds_read_b128 v[186:189], v99 offset:49152
	v_add_f32_e32 v98, v245, v98
	v_exp_f32_e32 v246, v100
	s_waitcnt lgkmcnt(3)
	v_mfma_f32_32x32x16_bf16 v[82:97], v[210:213], v[134:137], v[82:97]
	ds_read_b128 v[190:193], v99 offset:57344
	v_add_f32_e32 v248, v246, v98
	v_exp_f32_e32 v247, v101
	s_waitcnt lgkmcnt(3)
	v_mfma_f32_32x32x16_bf16 v[114:129], v[236:239], v[138:141], v[114:129]
	v_add_u32_e32 v210, v220, v225
	ds_read_b128 v[98:101], v210 offset:49152
	v_exp_f32_e32 v249, v102
	v_add_f32_e32 v102, v247, v248
	s_waitcnt lgkmcnt(3)
	v_mfma_f32_32x32x16_bf16 v[82:97], v[240:243], v[138:141], v[82:97]
	ds_read_b128 v[210:213], v210 offset:57344
	v_add_f32_e32 v102, v249, v102
	v_exp_f32_e32 v248, v103
	s_waitcnt lgkmcnt(3)
	v_mfma_f32_32x32x16_bf16 v[114:129], v[186:189], v[142:145], v[114:129]
	v_add_u32_e32 v103, v220, v224
	ds_read_b128 v[236:239], v103 offset:49152
	v_add_f32_e32 v102, v248, v102
	v_exp_f32_e32 v240, v104
	s_waitcnt lgkmcnt(3)
	v_mfma_f32_32x32x16_bf16 v[82:97], v[190:193], v[142:145], v[82:97]
	ds_read_b128 v[186:189], v103 offset:57344
	v_add_f32_e32 v242, v240, v102
	v_exp_f32_e32 v241, v105
	s_waitcnt lgkmcnt(3)
	v_mfma_f32_32x32x16_bf16 v[114:129], v[98:101], v[154:157], v[114:129]
	v_add_u32_e32 v190, v220, v223
	ds_read_b128 v[102:105], v190 offset:49152
	v_add_f32_e32 v98, v241, v242
	v_exp_f32_e32 v243, v106
	s_waitcnt lgkmcnt(3)
	v_mfma_f32_32x32x16_bf16 v[82:97], v[210:213], v[154:157], v[82:97]
	ds_read_b128 v[190:193], v190 offset:57344
	v_add_f32_e32 v100, v243, v98
	v_exp_f32_e32 v242, v107
	v_cvt_pk_bf16_f32 v98, v244, v245
	v_cvt_pk_bf16_f32 v99, v246, v247
	s_waitcnt lgkmcnt(3)
	v_mfma_f32_32x32x16_bf16 v[114:129], v[236:239], v[150:153], v[114:129]
	v_add_u32_e32 v106, v220, v222
	ds_read_b128 v[210:213], v106 offset:49152
	v_add_f32_e32 v107, v242, v100
	v_exp_f32_e32 v220, v108
	v_cvt_pk_bf16_f32 v100, v249, v248
	v_cvt_pk_bf16_f32 v101, v240, v241
	s_waitcnt lgkmcnt(3)
	v_mfma_f32_32x32x16_bf16 v[82:97], v[186:189], v[150:153], v[82:97]
	ds_read_b128 v[236:239], v106 offset:57344
	v_add_f32_e32 v241, v220, v107
	v_permlane32_swap_b32_e32 v98, v100
	v_permlane32_swap_b32_e32 v99, v101
	v_exp_f32_e32 v240, v109
	s_waitcnt lgkmcnt(3)
	v_mfma_f32_32x32x16_bf16 v[114:129], v[102:105], v[146:149], v[114:129]
	v_add_u32_e32 v186, v234, v221
	ds_read_b128 v[106:109], v186
	v_exp_f32_e32 v244, v110
	v_add_f32_e32 v110, v240, v241
	s_waitcnt lgkmcnt(3)
	v_mfma_f32_32x32x16_bf16 v[82:97], v[190:193], v[146:149], v[82:97]
	ds_read_b128 v[102:105], v186 offset:4096
	v_add_f32_e32 v110, v244, v110
	v_exp_f32_e32 v241, v111
	s_waitcnt lgkmcnt(3)
	v_mfma_f32_32x32x16_bf16 v[114:129], v[210:213], v[158:161], v[114:129]
	v_add_u32_e32 v111, v234, v209
	ds_read_b128 v[186:189], v111
	v_add_f32_e32 v110, v241, v110
	v_exp_f32_e32 v245, v112
	s_waitcnt lgkmcnt(3)
	v_mfma_f32_32x32x16_bf16 v[82:97], v[236:239], v[158:161], v[82:97]
	ds_read_b128 v[190:193], v111 offset:4096
	v_add_f32_e32 v210, v245, v110
	v_exp_f32_e32 v246, v113
	s_waitcnt lgkmcnt(3)
	v_mfma_f32_32x32x16_bf16 v[114:129], v[106:109], v[162:165], v[114:129]
	v_add_u32_e32 v211, v234, v208
	ds_read_b128 v[110:113], v211
	v_add_f32_e32 v236, v246, v210
	s_waitcnt lgkmcnt(3)
	v_mfma_f32_32x32x16_bf16 v[82:97], v[102:105], v[162:165], v[82:97]
	ds_read_b128 v[106:109], v211 offset:4096
	v_cvt_pk_bf16_f32 v102, v243, v242
	v_cvt_pk_bf16_f32 v103, v220, v240
	s_waitcnt lgkmcnt(3)
	v_mfma_f32_32x32x16_bf16 v[114:129], v[186:189], v[166:169], v[114:129]
	v_add_u32_e32 v220, v234, v207
	ds_read_b128 v[210:213], v220
	v_cvt_pk_bf16_f32 v104, v244, v241
	v_cvt_pk_bf16_f32 v105, v245, v246
	s_waitcnt lgkmcnt(3)
	v_mfma_f32_32x32x16_bf16 v[82:97], v[190:193], v[166:169], v[82:97]
	ds_read_b128 v[186:189], v220 offset:4096
	v_permlane32_swap_b32_e32 v102, v104
	v_permlane32_swap_b32_e32 v103, v105
	s_waitcnt lgkmcnt(3)
	v_mfma_f32_32x32x16_bf16 v[114:129], v[110:113], v[170:173], v[114:129]
	v_mov_b32_e32 v110, v236
	s_nop 1
	v_permlane32_swap_b32_e32 v236, v110
	v_add_f32_e32 v110, v236, v110
	v_add_f32_e32 v234, v1, v110
	s_waitcnt lgkmcnt(2)
	v_mfma_f32_32x32x16_bf16 v[82:97], v[106:109], v[170:173], v[82:97]
	ds_read_b64_tr_b16 v[110:111], v235
	ds_read_b64_tr_b16 v[112:113], v235 offset:2048
	s_waitcnt lgkmcnt(3)
	v_mfma_f32_32x32x16_bf16 v[114:129], v[210:213], v[174:177], v[114:129]
	ds_read_b64_tr_b16 v[236:237], v235 offset:512
	ds_read_b64_tr_b16 v[238:239], v235 offset:2560
	s_waitcnt lgkmcnt(4)
	v_mfma_f32_32x32x16_bf16 v[82:97], v[186:189], v[174:177], v[82:97]
	ds_read_b64_tr_b16 v[106:107], v235 offset:1024
	ds_read_b64_tr_b16 v[108:109], v235 offset:3072
	s_cmp_eq_u32 s100, 0
	s_cbranch_scc1 .Lmla_wbb2
	s_waitcnt vmcnt(0)
.Lmla_wbb2:
	s_barrier
	s_waitcnt lgkmcnt(4)
	v_mfma_f32_32x32x16_bf16 v[50:65], v[182:185], v[110:113], v[50:65]
	s_cmpk_lt_u32 s78, 0x7c
	s_cselect_b64 s[6:7], -1, 0
	s_add_i32 s8, s13, s76
	ds_read_b64_tr_b16 v[190:191], v235 offset:1536
	ds_read_b64_tr_b16 v[192:193], v235 offset:3584
	s_add_u32 s12, s18, 0x15018100
	s_addc_u32 s13, s19, 0
	s_add_i32 s1, s1, s73
	s_mov_b32 s9, m0
	s_mov_b32 m0, s1
	s_nop 0
	global_load_lds_dwordx4 v199, s[12:13]
	s_mov_b32 m0, s9
	s_add_u32 s18, s18, 0x1501c100
	s_addc_u32 s19, s19, 0
	s_add_i32 s5, s1, 0x2000
	s_cmpk_gt_u32 s78, 0x7b
	s_waitcnt lgkmcnt(4)
	v_mfma_f32_32x32x16_bf16 v[34:49], v[182:185], v[236:239], v[34:49]
	ds_read_b64_tr_b16 v[186:187], v235 offset:4096
	ds_read_b64_tr_b16 v[188:189], v235 offset:6144
	s_mov_b32 s1, m0
	s_mov_b32 m0, s5
	s_nop 0
	global_load_lds_dwordx4 v199, s[18:19]
	s_mov_b32 m0, s1
	ds_read_b64_tr_b16 v[110:111], v235 offset:4608
	ds_read_b64_tr_b16 v[112:113], v235 offset:6656
	s_cbranch_scc1 .LBB0_246
	s_add_u32 s12, s14, 0x20000
	s_addc_u32 s13, s15, 0
	s_mov_b32 s1, m0
	s_mov_b32 m0, s8
	s_nop 0
	global_load_lds_dwordx4 v197, s[12:13]
	s_mov_b32 m0, s1

.LBB0_261:
	s_waitcnt vmcnt(2) lgkmcnt(0)
	s_barrier
	s_add_i32 s0, 0, 0x10000
	v_add_u32_e32 v1, s0, v204
	v_add_u32_e32 v98, v1, v229
	ds_read_b128 v[114:117], v98
	ds_read_b128 v[118:121], v98 offset:8192
	v_add_u32_e32 v98, v1, v228
	ds_read_b128 v[122:125], v98
	ds_read_b128 v[126:129], v98 offset:8192
	s_waitcnt lgkmcnt(3)
	v_mfma_f32_32x32x16_bf16 v[98:113], v[114:117], v[130:133], v[66:81]
	v_add_u32_e32 v192, v1, v227
	ds_read_b128 v[188:191], v192
	s_add_i32 s0, 0, 0x1a000
	v_add_u32_e32 v187, s0, v205
	v_exp_f32_e32 v193, v82
	s_waitcnt lgkmcnt(3)
	v_mfma_f32_32x32x16_bf16 v[66:81], v[118:121], v[130:133], v[66:81]
	ds_read_b128 v[114:117], v192 offset:8192
	v_add_f32_e32 v82, v193, v186
	v_exp_f32_e32 v192, v83
	s_waitcnt lgkmcnt(3)
	v_mfma_f32_32x32x16_bf16 v[98:113], v[122:125], v[134:137], v[98:113]
	v_add_u32_e32 v83, v1, v226
	ds_read_b128 v[118:121], v83
	v_add_f32_e32 v82, v192, v82
	v_exp_f32_e32 v186, v84
	s_waitcnt lgkmcnt(3)
	v_mfma_f32_32x32x16_bf16 v[66:81], v[126:129], v[134:137], v[66:81]
	ds_read_b128 v[122:125], v83 offset:8192
	v_add_f32_e32 v130, v186, v82
	v_exp_f32_e32 v204, v85
	s_waitcnt lgkmcnt(3)
	v_mfma_f32_32x32x16_bf16 v[98:113], v[188:191], v[138:141], v[98:113]
	v_add_u32_e32 v126, v1, v225
	ds_read_b128 v[82:85], v126
	v_exp_f32_e32 v134, v86
	v_add_f32_e32 v86, v204, v130
	s_waitcnt lgkmcnt(3)
	v_mfma_f32_32x32x16_bf16 v[66:81], v[114:117], v[138:141], v[66:81]
	ds_read_b128 v[126:129], v126 offset:8192
	v_add_f32_e32 v86, v134, v86
	v_exp_f32_e32 v135, v87
	s_waitcnt lgkmcnt(3)
	v_mfma_f32_32x32x16_bf16 v[98:113], v[118:121], v[142:145], v[98:113]
	v_add_u32_e32 v87, v1, v224
	ds_read_b128 v[130:133], v87
	v_exp_f32_e32 v117, v88
	v_add_f32_e32 v86, v135, v86
	s_waitcnt lgkmcnt(3)
	v_mfma_f32_32x32x16_bf16 v[66:81], v[122:125], v[142:145], v[66:81]
	ds_read_b128 v[118:121], v87 offset:8192
	v_add_f32_e32 v114, v117, v86
	v_exp_f32_e32 v136, v89
	s_waitcnt lgkmcnt(3)
	v_mfma_f32_32x32x16_bf16 v[98:113], v[82:85], v[154:157], v[98:113]
	v_add_u32_e32 v115, v1, v223
	ds_read_b128 v[86:89], v115
	v_exp_f32_e32 v137, v90
	v_add_f32_e32 v90, v136, v114
	s_waitcnt lgkmcnt(3)
	v_mfma_f32_32x32x16_bf16 v[66:81], v[126:129], v[154:157], v[66:81]
	ds_read_b128 v[82:85], v115 offset:8192
	v_add_f32_e32 v90, v137, v90
	v_exp_f32_e32 v138, v91
	v_cvt_pk_bf16_f32 v114, v193, v192
	v_cvt_pk_bf16_f32 v115, v186, v204
	s_waitcnt lgkmcnt(3)
	v_mfma_f32_32x32x16_bf16 v[98:113], v[130:133], v[150:153], v[98:113]
	v_add_u32_e32 v1, v1, v222
	ds_read_b128 v[122:125], v1
	v_exp_f32_e32 v130, v92
	v_add_f32_e32 v90, v138, v90
	v_cvt_pk_bf16_f32 v116, v134, v135
	v_cvt_pk_bf16_f32 v117, v117, v136
	s_waitcnt lgkmcnt(3)
	v_mfma_f32_32x32x16_bf16 v[66:81], v[118:121], v[150:153], v[66:81]
	ds_read_b128 v[126:129], v1 offset:8192
	v_exp_f32_e32 v1, v93
	v_add_f32_e32 v131, v130, v90
	v_permlane32_swap_b32_e32 v114, v116
	v_permlane32_swap_b32_e32 v115, v117
	s_waitcnt lgkmcnt(3)
	v_mfma_f32_32x32x16_bf16 v[98:113], v[86:89], v[146:149], v[98:113]
	v_add_u32_e32 v118, v187, v221
	ds_read_b128 v[90:93], v118
	v_exp_f32_e32 v120, v94
	v_add_f32_e32 v94, v1, v131
	s_waitcnt lgkmcnt(3)
	v_mfma_f32_32x32x16_bf16 v[66:81], v[82:85], v[146:149], v[66:81]
	ds_read_b128 v[86:89], v118 offset:4096
	v_exp_f32_e32 v121, v95
	v_add_f32_e32 v94, v120, v94
	s_waitcnt lgkmcnt(3)
	v_mfma_f32_32x32x16_bf16 v[98:113], v[122:125], v[158:161], v[98:113]
	v_add_u32_e32 v95, v187, v209
	ds_read_b128 v[82:85], v95
	v_exp_f32_e32 v131, v96
	v_add_f32_e32 v94, v121, v94
	s_waitcnt lgkmcnt(3)
	v_mfma_f32_32x32x16_bf16 v[66:81], v[126:129], v[158:161], v[66:81]
	ds_read_b128 v[122:125], v95 offset:4096
	v_exp_f32_e32 v132, v97
	v_add_f32_e32 v118, v131, v94
	s_waitcnt lgkmcnt(3)
	v_mfma_f32_32x32x16_bf16 v[98:113], v[90:93], v[162:165], v[98:113]
	v_add_u32_e32 v119, v187, v208
	ds_read_b128 v[94:97], v119
	v_add_f32_e32 v126, v132, v118
	s_waitcnt lgkmcnt(3)
	v_mfma_f32_32x32x16_bf16 v[66:81], v[86:89], v[162:165], v[66:81]
	ds_read_b128 v[90:93], v119 offset:4096
	v_cvt_pk_bf16_f32 v118, v137, v138
	v_cvt_pk_bf16_f32 v119, v130, v1
	s_waitcnt lgkmcnt(3)
	v_mfma_f32_32x32x16_bf16 v[98:113], v[82:85], v[166:169], v[98:113]
	v_add_u32_e32 v1, v187, v207
	ds_read_b128 v[86:89], v1
	v_cvt_pk_bf16_f32 v120, v120, v121
	v_cvt_pk_bf16_f32 v121, v131, v132
	s_waitcnt lgkmcnt(3)
	v_mfma_f32_32x32x16_bf16 v[66:81], v[122:125], v[166:169], v[66:81]
	ds_read_b128 v[82:85], v1 offset:4096
	v_permlane32_swap_b32_e32 v118, v120
	v_permlane32_swap_b32_e32 v119, v121
	s_waitcnt lgkmcnt(3)
	v_mfma_f32_32x32x16_bf16 v[98:113], v[94:97], v[170:173], v[98:113]
	v_mov_b32_e32 v1, v126
	s_nop 1
	v_permlane32_swap_b32_e32 v126, v1
	v_add_f32_e32 v1, v126, v1
	v_add_f32_e32 v1, v234, v1
	s_waitcnt lgkmcnt(2)
	v_mfma_f32_32x32x16_bf16 v[66:81], v[90:93], v[170:173], v[66:81]
	ds_read_b64_tr_b16 v[94:95], v202
	ds_read_b64_tr_b16 v[96:97], v202 offset:2048
	s_waitcnt lgkmcnt(3)
	v_mfma_f32_32x32x16_bf16 v[98:113], v[86:89], v[174:177], v[98:113]
	ds_read_b64_tr_b16 v[90:91], v202 offset:512
	ds_read_b64_tr_b16 v[92:93], v202 offset:2560
	s_waitcnt lgkmcnt(4)
	v_mfma_f32_32x32x16_bf16 v[66:81], v[82:85], v[174:177], v[66:81]
	ds_read_b64_tr_b16 v[86:87], v202 offset:1024
	ds_read_b64_tr_b16 v[88:89], v202 offset:3072
	s_cmp_eq_u32 s100, 0
	s_cbranch_scc1 .Lmla_wbb3
	s_waitcnt vmcnt(0)
.Lmla_wbb3:
	s_barrier
	s_waitcnt lgkmcnt(4)
	v_mfma_f32_32x32x16_bf16 v[50:65], v[182:185], v[94:97], v[50:65]
	ds_read_b64_tr_b16 v[82:83], v202 offset:1536
	ds_read_b64_tr_b16 v[84:85], v202 offset:3584
	s_waitcnt lgkmcnt(4)
	v_mfma_f32_32x32x16_bf16 v[34:49], v[182:185], v[90:93], v[34:49]
	ds_read_b64_tr_b16 v[130:131], v202 offset:4096
	ds_read_b64_tr_b16 v[132:133], v202 offset:6144
	s_waitcnt lgkmcnt(4)
	v_mfma_f32_32x32x16_bf16 v[18:33], v[182:185], v[86:89], v[18:33]
	ds_read_b64_tr_b16 v[126:127], v202 offset:4608
	ds_read_b64_tr_b16 v[128:129], v202 offset:6656
	s_waitcnt lgkmcnt(4)
	v_mfma_f32_32x32x16_bf16 v[2:17], v[182:185], v[82:85], v[2:17]
	ds_read_b64_tr_b16 v[122:123], v202 offset:5120
	ds_read_b64_tr_b16 v[124:125], v202 offset:7168
	v_max_f32_e32 v82, v99, v99
	v_max_f32_e32 v83, v98, v98
	v_max_f32_e32 v82, v83, v82
	v_max3_f32 v83, v100, v101, v67
	v_max3_f32 v82, v82, v66, v68
	v_max3_f32 v82, v82, v69, v102
	v_max3_f32 v83, v83, v104, v105
	v_max3_f32 v82, v82, v103, v70
	v_max3_f32 v83, v83, v72, v73
	v_max3_f32 v82, v82, v71, v106
	v_max3_f32 v83, v83, v108, v109
	v_max3_f32 v82, v82, v107, v74
	v_max3_f32 v83, v83, v76, v77
	v_max3_f32 v82, v82, v75, v110
	v_max3_f32 v83, v83, v112, v113
	v_max3_f32 v82, v82, v111, v78
	v_max3_f32 v83, v83, v80, v81
	v_max3_f32 v82, v82, v79, v83
	v_mov_b32_e32 v83, v82
	s_nop 1
	v_permlane32_swap_b32_e32 v82, v83
	v_max_f32_e32 v83, v83, v83
	v_max_f32_e32 v82, v82, v82
	v_max_f32_e32 v82, v82, v83
	v_cmp_lt_f32_e32 vcc, s92, v82
	s_cmp_lg_u64 vcc, 0
	s_cselect_b64 s[6:7], -1, 0
	s_cbranch_vccnz .LBB0_268

; #define SBAR() __builtin_amdgcn_sched_barrier(0)
; __device__ __forceinline__ int v_rd_base(int lane) { return ((lane & 3) << 3) | (((lane >> 2) & 3) << 6) | (((lane >> 4) & 1) << 5) | (((lane >> 5) & 1) << 8); }
; #define WAIT_BAR(N) asm volatile("s_waitcnt vmcnt(" #N ") lgkmcnt(0)\n\ts_barrier" ::: "memory")
; template <int D0> __device__ __forceinline__ void pv_one(f32x16& od, int vb, bf16x8 pa0, bf16x8 pa1, bf16x8 pa2, bf16x8 pa3) {
;   const s16x4 l0 = tr_read<v_rd_off(D0, 0, 0)>(vb), h0 = tr_read<v_rd_off(D0, 0, 1)>(vb), l1 = tr_read<v_rd_off(D0, 1, 0)>(vb), h1 = tr_read<v_rd_off(D0, 1, 1)>(vb);
;   const s16x4 l2 = tr_read<v_rd_off(D0, 2, 0)>(vb), h2 = tr_read<v_rd_off(D0, 2, 1)>(vb), l3 = tr_read<v_rd_off(D0, 3, 0)>(vb), h3 = tr_read<v_rd_off(D0, 3, 1)>(vb);
;   asm volatile("s_waitcnt lgkmcnt(0)" ::: "memory"); SBAR();
;     ...
;   od = __builtin_amdgcn_mfma_f32_32x32x16_bf16(pa0, PK(l0, h0), od, 0, 0, 0);
;   od = __builtin_amdgcn_mfma_f32_32x32x16_bf16(pa1, PK(l1, h1), od, 0, 0, 0);
;   od = __builtin_amdgcn_mfma_f32_32x32x16_bf16(pa2, PK(l2, h2), od, 0, 0, 0);
;   od = __builtin_amdgcn_mfma_f32_32x32x16_bf16(pa3, PK(l3, h3), od, 0, 0, 0);
;     ...
; }
; __device__ __forceinline__ void pv_d0(f32x16* o, int vb, bf16x8 pa0, bf16x8 pa1, bf16x8 pa2, bf16x8 pa3) {
;   pv_one<0>(o[0], vb, pa0, pa1, pa2, pa3); pv_one<1>(o[1], vb, pa0, pa1, pa2, pa3); pv_one<2>(o[2], vb, pa0, pa1, pa2, pa3); pv_one<3>(o[3], vb, pa0, pa1, pa2, pa3);
; __device__ __forceinline__ void mla_unit(char* lds, const bf16_t* __restrict__ Qp, const bf16_t* __restrict__ Knp, const bf16_t* __restrict__ Vp, ...
;     ...
;   WAIT_BAR(0);
;   { EXP16(pB1); float s_ = sum0;
; #pragma unroll
;     for (int r = 0; r < 16; ++r) s_ += pB1[r];
;     auto rr_ = __builtin_amdgcn_permlane32_swap(__float_as_uint(s_), __float_as_uint(s_), false, false); l_reg += __uint_as_float(rr_[0]) + __uint_as_float(rr_[1]);
;     { unsigned a0_ = cvtpk(pB1[0], pB1[1]), a1_ = cvtpk(pB1[2], pB1[3]), b0_ = cvtpk(pB1[4], pB1[5]), b1_ = cvtpk(pB1[6], pB1[7]); PSWAP(a0_, a1_, b0_, b1_, pa2); }
;     { unsigned a0_ = cvtpk(pB1[8], pB1[9]), a1_ = cvtpk(pB1[10], pB1[11]), b0_ = cvtpk(pB1[12], pB1[13]), b1_ = cvtpk(pB1[14], pB1[15]); PSWAP(a0_, a1_, b0_, b1_, pa3); } }
;   SBAR();
;   pv_d0(o, (int)(lds0 + P_V) + v_rd_base(lane) + s0 * SHM_V, pa0, pa1, pa2, pa3);
;   asm volatile("s_waitcnt lgkmcnt(0)\n\ts_barrier" ::: "memory");
.LBB0_264:
	v_exp_f32_e32 v92, v66
	v_exp_f32_e32 v93, v67
	v_exp_f32_e32 v94, v68
	v_exp_f32_e32 v69, v69
	v_exp_f32_e32 v70, v70
	v_add_f32_e32 v66, v92, v91
	v_exp_f32_e32 v71, v71
	v_add_f32_e32 v66, v93, v66
	v_exp_f32_e32 v72, v72
	v_add_f32_e32 v66, v94, v66
	v_exp_f32_e32 v73, v73
	v_add_f32_e32 v66, v69, v66
	v_exp_f32_e32 v74, v74
	v_add_f32_e32 v66, v70, v66
	v_exp_f32_e32 v75, v75
	v_add_f32_e32 v66, v71, v66
	v_exp_f32_e32 v76, v76
	v_add_f32_e32 v66, v72, v66
	v_exp_f32_e32 v77, v77
	v_add_f32_e32 v66, v73, v66
	v_exp_f32_e32 v78, v78
	v_add_f32_e32 v66, v74, v66
	v_exp_f32_e32 v79, v79
	v_add_f32_e32 v66, v75, v66
	v_exp_f32_e32 v80, v80
	v_add_f32_e32 v66, v76, v66
	v_exp_f32_e32 v81, v81
	v_add_f32_e32 v66, v77, v66
	v_add_f32_e32 v66, v78, v66
	v_add_f32_e32 v66, v79, v66
	s_add_i32 s8, s74, s66
	v_add_f32_e32 v66, v80, v66
	s_cmpk_lt_i32 s8, 0x400
	s_waitcnt vmcnt(0) lgkmcnt(0)
	s_barrier
	v_add_f32_e32 v66, v81, v66
	s_cselect_b64 s[6:7], -1, 0
	s_cmpk_gt_i32 s8, 0x3ff
	v_mov_b32_e32 v67, v66
	s_cselect_b64 s[42:43], -1, 0
	s_nop 0
	v_permlane32_swap_b32_e32 v66, v67
	v_cvt_pk_bf16_f32 v68, v92, v93
	v_cvt_pk_bf16_f32 v69, v94, v69
	v_cvt_pk_bf16_f32 v70, v70, v71
	v_cvt_pk_bf16_f32 v71, v72, v73
	v_cvt_pk_bf16_f32 v72, v74, v75
	v_cvt_pk_bf16_f32 v73, v76, v77
	v_cvt_pk_bf16_f32 v74, v78, v79
	v_cvt_pk_bf16_f32 v75, v80, v81
	s_nop 0
	v_permlane32_swap_b32_e32 v68, v70
	v_permlane32_swap_b32_e32 v69, v71
	v_permlane32_swap_b32_e32 v72, v74
	v_permlane32_swap_b32_e32 v73, v75
	s_cmp_lg_u32 0, -1
	s_cselect_b32 s0, 0, 0
	s_addk_i32 s0, 0x4000
	v_add_u32_e32 v80, s0, v201
	ds_read_b64_tr_b16 v[76:77], v80 offset:0
	ds_read_b64_tr_b16 v[78:79], v80 offset:0x800
	ds_read_b64_tr_b16 v[92:93], v80 offset:0x1000
	ds_read_b64_tr_b16 v[94:95], v80 offset:0x1800
	ds_read_b64_tr_b16 v[96:97], v80 offset:0x2000
	ds_read_b64_tr_b16 v[98:99], v80 offset:0x2800
	ds_read_b64_tr_b16 v[100:101], v80 offset:0x3000
	ds_read_b64_tr_b16 v[102:103], v80 offset:0x3800
	s_waitcnt lgkmcnt(0)
	s_nop 0
	v_mfma_f32_32x32x16_bf16 v[50:65], v[82:85], v[76:79], v[50:65]
	ds_read_b64_tr_b16 v[76:77], v80 offset:0x200
	ds_read_b64_tr_b16 v[78:79], v80 offset:0xa00
	v_mfma_f32_32x32x16_bf16 v[50:65], v[86:89], v[92:95], v[50:65]
	ds_read_b64_tr_b16 v[92:93], v80 offset:0x1200
	ds_read_b64_tr_b16 v[94:95], v80 offset:0x1a00
	v_mfma_f32_32x32x16_bf16 v[50:65], v[68:71], v[96:99], v[50:65]
	ds_read_b64_tr_b16 v[96:97], v80 offset:0x2200
	ds_read_b64_tr_b16 v[98:99], v80 offset:0x2a00
	v_mfma_f32_32x32x16_bf16 v[50:65], v[72:75], v[100:103], v[50:65]
	ds_read_b64_tr_b16 v[100:101], v80 offset:0x3200
	ds_read_b64_tr_b16 v[102:103], v80 offset:0x3a00
	s_waitcnt lgkmcnt(0)
	v_mfma_f32_32x32x16_bf16 v[34:49], v[82:85], v[76:79], v[34:49]
	ds_read_b64_tr_b16 v[76:77], v80 offset:0x400
	ds_read_b64_tr_b16 v[78:79], v80 offset:0xc00
	v_mfma_f32_32x32x16_bf16 v[34:49], v[86:89], v[92:95], v[34:49]
	ds_read_b64_tr_b16 v[92:93], v80 offset:0x1400
	ds_read_b64_tr_b16 v[94:95], v80 offset:0x1c00
	v_mfma_f32_32x32x16_bf16 v[34:49], v[68:71], v[96:99], v[34:49]
	ds_read_b64_tr_b16 v[96:97], v80 offset:0x2400
	ds_read_b64_tr_b16 v[98:99], v80 offset:0x2c00
	v_mfma_f32_32x32x16_bf16 v[34:49], v[72:75], v[100:103], v[34:49]
	ds_read_b64_tr_b16 v[100:101], v80 offset:0x3400
	ds_read_b64_tr_b16 v[102:103], v80 offset:0x3c00
	s_waitcnt lgkmcnt(0)
	v_mfma_f32_32x32x16_bf16 v[18:33], v[82:85], v[76:79], v[18:33]
	ds_read_b64_tr_b16 v[76:77], v80 offset:0x600
	ds_read_b64_tr_b16 v[78:79], v80 offset:0xe00
	v_mfma_f32_32x32x16_bf16 v[18:33], v[86:89], v[92:95], v[18:33]
	ds_read_b64_tr_b16 v[92:93], v80 offset:0x1600
	ds_read_b64_tr_b16 v[94:95], v80 offset:0x1e00
	v_mfma_f32_32x32x16_bf16 v[18:33], v[68:71], v[96:99], v[18:33]
	ds_read_b64_tr_b16 v[96:97], v80 offset:0x2600
	ds_read_b64_tr_b16 v[98:99], v80 offset:0x2e00
	v_mfma_f32_32x32x16_bf16 v[18:33], v[72:75], v[100:103], v[18:33]
	ds_read_b64_tr_b16 v[100:101], v80 offset:0x3600
	ds_read_b64_tr_b16 v[102:103], v80 offset:0x3e00
	s_waitcnt lgkmcnt(0)
	v_mfma_f32_32x32x16_bf16 v[2:17], v[82:85], v[76:79], v[2:17]
	s_cmp_lg_u32 s100, 0
	s_cbranch_scc1 .Lmla_noXp
	s_barrier
; #define DMA_K2(KB, RB, t, slot) do { const bf16_t* s_ = (KB) + (long)(t) * (KVBLK * LDK); const unsigned d_ = (unsigned)__builtin_amdgcn_readfirstlane(kn_dst + (slot) * SHM_KN); \
;     glds16s(s_, kn_off, d_); glds16s(s_ + 16 * LDK, kn_off, d_ + 4096); glds16s((RB) + (long)(t) * (KVBLK * 64), kr_off, (unsigned)__builtin_amdgcn_readfirstlane(kr_dst + (slot) * SHM_KR)); } while (0)
; #define DMA_V2(VB, t, slot) do { const bf16_t* s_ = (VB) + (long)(t) * (KVBLK * LDK); const unsigned d_ = (unsigned)__builtin_amdgcn_readfirstlane(v_dst + (slot) * SHM_V); \
;     glds16s(s_, v_off, d_); glds16s(s_ + 32 * LDK, v_off, d_ + 8192); } while (0)
; __device__ __forceinline__ void mla_unit(char* lds, const bf16_t* __restrict__ Qp, const bf16_t* __restrict__ Knp, const bf16_t* __restrict__ Vp, ...
;     ...
;   asm volatile("s_waitcnt lgkmcnt(0)\n\ts_barrier" ::: "memory");
;   if (has_next) { DMA_K2(nKnp, nKrp, 0, 0); DMA_V2(nVp, 0, 0); DMA_K2(nKnp, nKrp, 1, 1); DMA_V2(nVp, 1, 1); DMA_K2(nKnp, nKrp, 2, 2); }
.Lmla_noXp:
	s_waitcnt lgkmcnt(0)
	s_barrier
	s_and_b64 vcc, exec, s[42:43]
	v_mfma_f32_32x32x16_bf16 v[2:17], v[86:89], v[92:95], v[2:17]
	v_mfma_f32_32x32x16_bf16 v[2:17], v[68:71], v[96:99], v[2:17]
	v_mfma_f32_32x32x16_bf16 v[2:17], v[72:75], v[100:103], v[2:17]
	s_cbranch_vccnz .LBB0_266
	s_and_b64 s[0:1], s[6:7], exec
	s_cselect_b32 s5, s8, s74
	s_ashr_i32 s0, s5, 9
	s_lshl_b32 s5, s5, 18
	s_ashr_i32 s1, s0, 31
	s_and_b32 s5, s5, 0x7800000
	v_readlane_b32 s6, v254, 62
	s_add_u32 s5, s6, s5
	v_readlane_b32 s6, v254, 63
	s_addc_u32 s9, s6, 0
	s_lshl_b64 s[6:7], s[0:1], 22
	s_add_u32 s6, s5, s6
	s_addc_u32 s7, s9, s7
	s_add_u32 s12, s6, 0x100
	s_addc_u32 s13, s7, 0
	s_lshl_b64 s[0:1], s[0:1], 20
	s_add_u32 s0, s26, s0
	s_addc_u32 s1, s27, s1
	s_mov_b32 s5, m0
	s_mov_b32 m0, s76
	s_nop 0
	global_load_lds_dwordx4 v197, s[6:7]
	s_mov_b32 m0, s5
	s_add_u32 s14, s6, 0x2000
	s_addc_u32 s15, s7, 0
	s_add_i32 s5, s76, 0x1000
	s_mov_b32 s9, m0
	s_mov_b32 m0, s5
	s_nop 0
	global_load_lds_dwordx4 v197, s[14:15]
	s_mov_b32 m0, s9
	s_mov_b32 s5, m0
	s_mov_b32 m0, s75
	s_nop 0
	global_load_lds_dwordx4 v198, s[0:1]
	s_mov_b32 m0, s5
	s_nop 0
	s_mov_b32 s5, m0
	s_mov_b32 m0, s73
	s_nop 0
	global_load_lds_dwordx4 v199, s[12:13]
	s_mov_b32 m0, s5
	s_add_u32 s12, s6, 0x4100
	s_addc_u32 s13, s7, 0
	s_add_i32 s5, s73, 0x2000
	s_mov_b32 s9, m0
	s_mov_b32 m0, s5
	s_nop 0
	global_load_lds_dwordx4 v199, s[12:13]
	s_mov_b32 m0, s9
	s_add_u32 s12, s6, 0x8000
	s_addc_u32 s13, s7, 0
	s_cmp_lg_u32 0, -1
	s_cselect_b32 s5, 0, 0
	s_add_i32 s9, s5, s72
	s_add_i32 s14, s9, 0x10000
	s_mov_b32 s15, m0
	s_mov_b32 m0, s14
	s_nop 0
	global_load_lds_dwordx4 v197, s[12:13]
	s_mov_b32 m0, s15
	s_add_u32 s12, s6, 0xa000
	s_addc_u32 s13, s7, 0
	s_add_i32 s14, s9, 0x11000
	s_mov_b32 s15, m0
	s_mov_b32 m0, s14
	s_nop 0
	global_load_lds_dwordx4 v197, s[12:13]
	s_mov_b32 m0, s15
	s_add_u32 s12, s0, 0x2000
	s_addc_u32 s13, s1, 0
	s_add_i32 s5, s5, s71
	s_add_i32 s14, s5, 0x1a000
	s_mov_b32 s15, m0
	s_mov_b32 m0, s14
	s_nop 0
	global_load_lds_dwordx4 v198, s[12:13]
	s_mov_b32 m0, s15
	s_add_u32 s12, s6, 0x8100
	s_addc_u32 s13, s7, 0
	s_add_i32 s14, s5, 0x4000
	s_mov_b32 s15, m0
	s_mov_b32 m0, s14
	s_nop 0
	global_load_lds_dwordx4 v199, s[12:13]
	s_mov_b32 m0, s15
	s_add_u32 s12, s6, 0xc100
	s_addc_u32 s13, s7, 0
	s_add_i32 s14, s5, 0x6000
	s_mov_b32 s15, m0
	s_mov_b32 m0, s14
	s_nop 0
	global_load_lds_dwordx4 v199, s[12:13]
	s_mov_b32 m0, s15
	s_add_u32 s12, s6, 0x10000
	s_addc_u32 s13, s7, 0
	s_add_i32 s14, s9, 0x14000
	s_add_u32 s6, s6, 0x12000
	s_mov_b32 s15, m0
	s_mov_b32 m0, s14
	s_nop 0
	global_load_lds_dwordx4 v197, s[12:13]
	s_mov_b32 m0, s15
	s_addc_u32 s7, s7, 0
	s_add_i32 s9, s9, 0x15000
	s_mov_b32 s12, m0
	s_mov_b32 m0, s9
	s_nop 0
	global_load_lds_dwordx4 v197, s[6:7]
	s_mov_b32 m0, s12
	s_add_u32 s0, s0, 0x4000
	s_addc_u32 s1, s1, 0
	s_add_i32 s5, s5, 0x1c000
	s_mov_b32 s6, m0
	s_mov_b32 m0, s5
	s_nop 0
	global_load_lds_dwordx4 v198, s[0:1]
	s_mov_b32 m0, s6

; __global__ void __launch_bounds__(NWAVES * 64, 2) fwd_mega(Args args) {
	.amdhsa_kernel _Z8fwd_mega4Args
		.amdhsa_group_segment_fixed_size 0
		.amdhsa_private_segment_fixed_size 0
		.amdhsa_kernarg_size 376
		.amdhsa_user_sgpr_count 2
		.amdhsa_user_sgpr_dispatch_ptr 0
		.amdhsa_user_sgpr_queue_ptr 0
		.amdhsa_user_sgpr_kernarg_segment_ptr 1
		.amdhsa_user_sgpr_dispatch_id 0
		.amdhsa_user_sgpr_kernarg_preload_length 0
		.amdhsa_user_sgpr_kernarg_preload_offset 0
		.amdhsa_user_sgpr_private_segment_size 0
		.amdhsa_uses_dynamic_stack 0
		.amdhsa_enable_private_segment 0
		.amdhsa_system_sgpr_workgroup_id_x 1
		.amdhsa_system_sgpr_workgroup_id_y 0
		.amdhsa_system_sgpr_workgroup_id_z 0
		.amdhsa_system_sgpr_workgroup_info 0
		.amdhsa_system_vgpr_workitem_id 2
		.amdhsa_next_free_vgpr 256
		.amdhsa_next_free_sgpr 102
		.amdhsa_accum_offset 256
		.amdhsa_reserve_vcc 1
		.amdhsa_float_round_mode_32 0
		.amdhsa_float_round_mode_16_64 0
		.amdhsa_float_denorm_mode_32 3
		.amdhsa_float_denorm_mode_16_64 3
		.amdhsa_dx10_clamp 1
		.amdhsa_ieee_mode 1
		.amdhsa_fp16_overflow 0
		.amdhsa_tg_split 0
		.amdhsa_exception_fp_ieee_invalid_op 0
		.amdhsa_exception_fp_denorm_src 0
		.amdhsa_exception_fp_ieee_div_zero 0
		.amdhsa_exception_fp_ieee_overflow 0
		.amdhsa_exception_fp_ieee_underflow 0
		.amdhsa_exception_fp_ieee_inexact 0
		.amdhsa_exception_int_div_zero 0
	.end_amdhsa_kernel

; __global__ void __launch_bounds__(NWAVES * 64, 2) fwd_mega(Args args) {
amdhsa.kernels:
  - .agpr_count:     0
    .args:
      - .offset:         0
        .size:           120
        .value_kind:     by_value
      - .offset:         120
        .size:           4
        .value_kind:     hidden_block_count_x
      - .offset:         124
        .size:           4
        .value_kind:     hidden_block_count_y
      - .offset:         128
        .size:           4
        .value_kind:     hidden_block_count_z
      - .offset:         132
        .size:           2
        .value_kind:     hidden_group_size_x
      - .offset:         134
        .size:           2
        .value_kind:     hidden_group_size_y
      - .offset:         136
        .size:           2
        .value_kind:     hidden_group_size_z
      - .offset:         138
        .size:           2
        .value_kind:     hidden_remainder_x
      - .offset:         140
        .size:           2
        .value_kind:     hidden_remainder_y
      - .offset:         142
        .size:           2
        .value_kind:     hidden_remainder_z
      - .offset:         160
        .size:           8
        .value_kind:     hidden_global_offset_x
      - .offset:         168
        .size:           8
        .value_kind:     hidden_global_offset_y
      - .offset:         176
        .size:           8
        .value_kind:     hidden_global_offset_z
      - .offset:         184
        .size:           2
        .value_kind:     hidden_grid_dims
      - .offset:         208
        .size:           8
        .value_kind:     hidden_multigrid_sync_arg
      - .offset:         240
        .size:           4
        .value_kind:     hidden_dynamic_lds_size
    .group_segment_fixed_size: 0
    .kernarg_segment_align: 8
    .kernarg_segment_size: 376
    .language:       OpenCL C
    .language_version:
      - 2
      - 0
    .max_flat_workgroup_size: 512
    .name:           _Z8fwd_mega4Args
    .private_segment_fixed_size: 0
    .sgpr_count:     108
    .sgpr_spill_count: 146
    .symbol:         _Z8fwd_mega4Args.kd
    .uniform_work_group_size: 1
    .uses_dynamic_stack: false
    .vgpr_count:     256
    .vgpr_spill_count: 0
    .wavefront_size: 64
